# decay product of each 8-token chunk folded into the recurrence operands by the preparation: recurrence step without the S*w multiply and without the w read (renormalised every 8 steps)
# speedup vs baseline: 1.0190x; 1.0113x over previous
; __device__ __forceinline__ float bf2f(bf16_t b) { return __uint_as_float(((unsigned)b) << 16); }
; __device__ __forceinline__ void p2_rwkv_prep(const Params& P, float* lds) {
;     ...
;     for (int it = 0; ch < NCHK; ch += NPREP, ++it) {
;         const int tok0 = ch * CT;
;         float* bufc = xbuf + (it & 1) * (CT * 128); float* bufn = xbuf + ((it + 1) & 1) * (CT * 128);
;         float nr[4], nk[4], nv[4], qr = 0.f, qk = 0.f, qv = 0.f;
;         if (tid < RW) {
; #pragma unroll
;             for (int q = 0; q < 4; ++q) { const bf16_t* p = prw + (size_t)(tok0 + q) * RCOLS + tid; nr[q] = bf2f(p[0]); nk[q] = bf2f(p[RW]); nv[q] = bf2f(p[2 * RW]); }
;             if (tok0 < NTOK && (tok0 & (SEQ - 1))) { const bf16_t* p = prw + (size_t)(tok0 - 1) * RCOLS + tid; qr = bf2f(p[0]); qk = bf2f(p[RW]); qv = bf2f(p[2 * RW]); }
;         }
.LBB0_764:
	s_cmpk_gt_i32 s30, 0x7ff
	s_cselect_b64 s[98:99], -1, 0
	v_mov_b32_e32 v255, 1.0
	s_add_i32 s31, s23, 0xfffffaa1
	v_mov_b32_e32 v131, 0
	v_mov_b32_e32 v130, 0
	v_mov_b32_e32 v1, 0
	s_and_saveexec_b64 s[0:1], s[4:5]
	s_cbranch_execz .LBB0_768
	v_mad_u64_u32 v[130:131], s[2:3], s31, v208, v[176:177]
	s_add_i32 s2, s23, 0xfffffaa2
	s_nop 0
	v_mad_u64_u32 v[134:135], s[2:3], s2, v208, v[176:177]
	s_add_i32 s2, s23, 0xfffffaa3
	s_nop 0
	v_mad_u64_u32 v[146:147], s[2:3], s2, v208, v[176:177]
	global_load_ushort v141, v[130:131], off
	global_load_ushort v144, v[130:131], off offset:768
	global_load_ushort v139, v[134:135], off
	global_load_ushort v142, v[134:135], off offset:768
	s_nop 0
	global_load_ushort v135, v[134:135], off offset:1536
	s_nop 0
	global_load_ushort v134, v[146:147], off
	global_load_ushort v138, v[146:147], off offset:768
	global_load_ushort v143, v[130:131], off offset:1536
	s_add_i32 s2, s23, 0xfffffaa4
	v_mad_u64_u32 v[130:131], s[2:3], s2, v208, v[176:177]
	global_load_ushort v136, v[130:131], off
	global_load_ushort v140, v[130:131], off offset:768
	global_load_ushort v132, v[130:131], off offset:1536
	global_load_ushort v137, v[146:147], off offset:1536
	s_cmpk_gt_i32 s30, 0x7ff
	s_cselect_b64 s[2:3], -1, 0
	s_and_b32 s16, s30, 0x1ff
	s_cmp_eq_u32 s16, 0
	s_cselect_b64 s[16:17], -1, 0
	s_or_b64 s[2:3], s[2:3], s[16:17]
	v_mov_b32_e32 v1, 0
	s_and_b64 vcc, exec, s[2:3]
	v_mov_b32_e32 v130, 0
	v_mov_b32_e32 v131, 0
	s_cbranch_vccnz .LBB0_767
	s_add_i32 s2, s23, 0xfffffaa0
	v_mad_i64_i32 v[130:131], s[2:3], s2, v208, v[176:177]
	global_load_ushort v1, v[130:131], off
	global_load_ushort v145, v[130:131], off offset:1536
	global_load_ushort v146, v[130:131], off offset:768
	s_waitcnt vmcnt(0)
	v_lshlrev_b32_e32 v131, 16, v1
	v_lshlrev_b32_e32 v130, 16, v145
	v_lshlrev_b32_e32 v1, 16, v146

; __device__ __forceinline__ float bf2f(bf16_t b) { return __uint_as_float(((unsigned)b) << 16); }
; __device__ __forceinline__ float sigmoidf_(float x) { return 1.f / (1.f + __expf(-x)); }
; __device__ __forceinline__ void p2_rwkv_prep(const Params& P, float* lds) {
;     ...
;             for (int tk = tg; tk < tg + 4; ++tk) {
;                 const int tok = tok0 + tk;
;                 if (tok >= NTOK) { const float* p = P.state_shift + (size_t)(tok - NTOK) * RCOLS + tid; qr = p[0]; qk = p[RW]; qv = p[2 * RW]; }
;                 const float cr = nr[tk & 3], ck = nk[tk & 3], cv = nv[tk & 3];
;                 if (tk + 4 < CT) { const bf16_t* p = prw + (size_t)(tok + 4) * RCOLS + tid; nr[tk & 3] = bf2f(p[0]); nk[tk & 3] = bf2f(p[RW]); nv[tk & 3] = bf2f(p[2 * RW]); }
;                 const float r = cr + (qr - cr) * mur, kraw = ck + (qk - ck) * muk, v = cv + (qv - cv) * muv;
;                 qr = cr; qk = ck; qv = cv;
;                 const float aw = w0c + yt[tk * 64 + cc], aa = a0c + yt[(CT + tk) * 64 + cc];
;                 const float w = __expf(-DECAY_SCALE * sigmoidf_(aw)), a = sigmoidf_(aa);
;                 const float kkv = kraw * kkc;
;                 const float n2 = wave_sum_fast(kkv * kkv);
;                 const float kk = kkv * rsqrtf(fmaxf(n2, 1e-12f));
;                 const float kmod = kraw * (1.f + (a - 1.f) * kac);
;                 const float bb = kk * a;
;                 const float br = wave_sum_fast(bb * r);
;                 ekk[tk - tg] = kk; ew[tk - tg] = w; ebb[tk - tg] = bb; ekm[tk - tg] = kmod; ewr[tk - tg] = w * r - kk * br; ev[tk - tg] = v;
;                 ebr[tk - tg] = br; ekr[tk - tg] = wave_sum_fast(kmod * r); erk[tk - tg] = wave_sum_fast(r * kmod * rkc);
;             }
; #pragma unroll
;             for (int tk = tg; tk < tg + 4; ++tk) {
;                 float* blk = RSB + ((size_t)(tok0 + tk) * RH + h) * RSB_BLK;
;                 float* oq = ot + (tk & 1) * 384;
;                 oq[cc] = ekk[tk - tg]; oq[64 + cc] = ew[tk - tg]; oq[128 + cc] = ebb[tk - tg]; oq[192 + cc] = ekm[tk - tg]; oq[256 + cc] = ewr[tk - tg]; oq[320 + cc] = ev[tk - tg];
;                 __builtin_amdgcn_wave_barrier();
;                 *(float4*)(blk + 4 * lane) = *(const float4*)(oq + 4 * lane);
;                 if (lane < 32) *(float4*)(blk + 256 + 4 * lane) = *(const float4*)(oq + 256 + 4 * lane);
.LBB0_793:
	v_add_f32_e32 v1, v190, v134
	v_mul_f32_e32 v1, 0xbfb8aa3b, v1
	v_exp_f32_e32 v1, v1
	v_sub_f32_e32 v153, v130, v213
	v_pk_add_f32 v[134:135], v[136:137], v[150:151]
	s_add_i32 s21, s23, 0xfffffaa8
	v_add_f32_e32 v1, 1.0, v1
	v_div_scale_f32 v130, s[2:3], v1, v1, 1.0
	v_rcp_f32_e32 v131, v130
	v_div_scale_f32 v136, vcc, 1.0, v1, 1.0
	s_waitcnt vmcnt(1)
	v_sub_f32_e32 v151, v185, v183
	v_fma_f32 v137, -v130, v131, 1.0
	v_fmac_f32_e32 v131, v137, v131
	v_mul_f32_e32 v137, v136, v131
	v_fma_f32 v150, -v130, v137, v136
	v_fmac_f32_e32 v137, v150, v131
	v_fma_f32 v130, -v130, v137, v136
	v_div_fmas_f32 v130, v130, v131, v137
	v_div_fixup_f32 v1, v130, v1, 1.0
	v_mul_f32_e32 v1, 0xbf1b4598, v1
	v_mul_f32_e32 v1, 0x3fb8aa3b, v1
	ds_read2st64_b32 v[130:131], v199 offset0:35 offset1:43
	v_exp_f32_e32 v228, v1
	v_mul_f32_e32 v1, v132, v134
	v_mad_u64_u32 v[136:137], s[2:3], s21, v208, v[176:177]
	v_fma_f32 v229, v152, v228, -v1
	s_waitcnt lgkmcnt(0)
	v_add_f32_e32 v1, v194, v131
	v_mul_f32_e32 v1, 0xbfb8aa3b, v1
	v_exp_f32_e32 v150, v1
	global_load_ushort v165, v[136:137], off
	global_load_ushort v166, v[136:137], off offset:768
	global_load_ushort v1, v[136:137], off offset:1536
	v_mov_b32_e32 v152, v183
	v_fmac_f32_e32 v152, v195, v151
	v_add_f32_e32 v136, 1.0, v150
	v_div_scale_f32 v137, s[2:3], v136, v136, 1.0
	v_rcp_f32_e32 v150, v137
	v_fmac_f32_e32 v213, v191, v153
	v_sub_f32_e32 v131, v184, v182
	v_fma_f32 v131, v196, v131, v182
	v_fma_f32 v151, -v137, v150, 1.0
	v_fmac_f32_e32 v150, v151, v150
	v_div_scale_f32 v151, vcc, 1.0, v136, 1.0
	v_mul_f32_e32 v153, v151, v150
	v_fma_f32 v184, -v137, v153, v151
	v_fmac_f32_e32 v153, v184, v150
	v_fma_f32 v137, -v137, v153, v151
	v_mul_f32_e32 v151, v193, v152
	v_mul_f32_e32 v184, v151, v151
	v_div_fmas_f32 v137, v137, v150, v153
	v_div_fixup_f32 v136, v137, v136, 1.0
	v_mov_b32_dpp v184, v184 quad_perm:[1,0,3,2] row_mask:0xf bank_mask:0xf bound_ctrl:1
	v_fmac_f32_e32 v184, v151, v151
	v_add_f32_e32 v137, -1.0, v136
	v_fma_f32 v137, v192, v137, 1.0
	v_add_f32_dpp v184, v184, v184 quad_perm:[2,3,0,1] row_mask:0xf bank_mask:0xf bound_ctrl:1
	s_mul_hi_u32 s35, s31, 6
	s_mul_i32 s31, s31, 6
	v_add_f32_dpp v184, v184, v184 row_ror:4 row_mask:0xf bank_mask:0xf bound_ctrl:1
	v_mul_f32_e32 v253, v132, v255
	v_mul_f32_e32 v254, v228, v255
	ds_write2st64_b32 v200, v253, v254 offset0:160 offset1:161
	v_mul_f32_e32 v253, v229, v255
	ds_write2st64_b32 v200, v253, v213 offset0:164 offset1:165
	v_cndmask_b32_e64 v255, v254, 1.0, s[98:99]
	v_rcp_f32_e32 v254, v255
	s_nop 0
	v_mul_f32_e32 v253, v155, v254
	v_mul_f32_e32 v254, v154, v254
	ds_write2st64_b32 v200, v253, v254 offset0:162 offset1:163
	v_add_f32_dpp v184, v184, v184 row_ror:8 row_mask:0xf bank_mask:0xf bound_ctrl:1
	v_mov_b32_e32 v185, v184
	s_nop 1
	v_permlane16_swap_b32_e32 v184, v185
	v_add_f32_e32 v184, v184, v185
	v_mov_b32_e32 v185, v184
	s_nop 1
	v_permlane32_swap_b32_e32 v184, v185
	v_add_f32_e32 v184, v184, v185
	v_max_f32_e32 v184, 0x2b8cbccc, v184
	v_rsq_f32_e32 v184, v184
	v_mul_f32_e32 v185, v152, v137
	ds_read_b128 v[228:231], v201
	v_or_b32_e32 v232, s31, v170
	v_mul_f32_e32 v184, v151, v184
	v_mul_f32_e32 v225, v136, v184
	v_mul_f32_e32 v136, v131, v225
	v_lshlrev_b32_e32 v132, 2, v172
	s_nop 0
	v_mov_b32_dpp v136, v136 quad_perm:[1,0,3,2] row_mask:0xf bank_mask:0xf bound_ctrl:1
	v_fmac_f32_e32 v136, v131, v225
	s_nop 1
	v_add_f32_dpp v136, v136, v136 quad_perm:[2,3,0,1] row_mask:0xf bank_mask:0xf bound_ctrl:1
	s_nop 1
	v_add_f32_dpp v136, v136, v136 row_ror:4 row_mask:0xf bank_mask:0xf bound_ctrl:1
	s_nop 1
	v_add_f32_dpp v136, v136, v136 row_ror:8 row_mask:0xf bank_mask:0xf bound_ctrl:1
	v_mov_b32_e32 v137, v136
	s_nop 1
	v_permlane16_swap_b32_e32 v136, v137
	v_add_f32_e32 v150, v136, v137
	v_mul_f32_e32 v136, v131, v185
	v_mov_b32_e32 v152, v150
	s_nop 1
	v_permlane32_swap_b32_e32 v150, v152
	v_mov_b32_dpp v137, v136 quad_perm:[1,0,3,2] row_mask:0xf bank_mask:0xf bound_ctrl:1
	v_fmac_f32_e32 v137, v131, v185
	s_nop 1
	v_add_f32_dpp v137, v137, v137 quad_perm:[2,3,0,1] row_mask:0xf bank_mask:0xf bound_ctrl:1
	s_nop 1
	v_add_f32_dpp v137, v137, v137 row_ror:4 row_mask:0xf bank_mask:0xf bound_ctrl:1
	s_nop 1
	v_add_f32_dpp v137, v137, v137 row_ror:8 row_mask:0xf bank_mask:0xf bound_ctrl:1
	v_mov_b32_e32 v151, v137
	s_nop 1
	v_permlane16_swap_b32_e32 v137, v151
	v_add_f32_e32 v151, v137, v151
	v_mul_f32_e32 v137, v197, v136
	v_mov_b32_e32 v153, v151
	s_nop 1
	v_permlane32_swap_b32_e32 v151, v153
	v_mov_b32_dpp v137, v137 quad_perm:[1,0,3,2] row_mask:0xf bank_mask:0xf bound_ctrl:1
	v_fmac_f32_e32 v137, v197, v136
	s_nop 1
	v_add_f32_dpp v136, v137, v137 quad_perm:[2,3,0,1] row_mask:0xf bank_mask:0xf bound_ctrl:1
	s_nop 1
	v_add_f32_dpp v136, v136, v136 row_ror:4 row_mask:0xf bank_mask:0xf bound_ctrl:1
	s_nop 1
	v_add_f32_dpp v136, v136, v136 row_ror:8 row_mask:0xf bank_mask:0xf bound_ctrl:1
	v_mov_b32_e32 v137, v136
	s_nop 1
	v_permlane16_swap_b32_e32 v136, v137
	v_add_f32_e32 v226, v136, v137
	v_mov_b64_e32 v[136:137], s[18:19]
	v_mad_u64_u32 v[154:155], s[2:3], v232, s25, v[136:137]
	v_mov_b32_e32 v227, v226
	v_mad_u32_u24 v155, s35, v211, v155
	s_nop 0
	v_permlane32_swap_b32_e32 v226, v227
	v_lshl_add_u64 v[136:137], v[154:155], 0, v[132:133]
	s_waitcnt lgkmcnt(0)
	global_store_dwordx4 v[136:137], v[228:231], off
	s_and_saveexec_b64 s[2:3], s[10:11]
	s_cbranch_execz .LBB0_795
	ds_read_b128 v[228:231], v202
	s_waitcnt lgkmcnt(0)
	global_store_dwordx4 v[136:137], v[228:231], off offset:1024

; __device__ __forceinline__ void p2_rwkv_prep(const Params& P, float* lds) {
;     ...
;             for (int tk = tg; tk < tg + 4; ++tk) {
;                 float* blk = RSB + ((size_t)(tok0 + tk) * RH + h) * RSB_BLK;
;                 float* oq = ot + (tk & 1) * 384;
;                 oq[cc] = ekk[tk - tg]; oq[64 + cc] = ew[tk - tg]; oq[128 + cc] = ebb[tk - tg]; oq[192 + cc] = ekm[tk - tg]; oq[256 + cc] = ewr[tk - tg]; oq[320 + cc] = ev[tk - tg];
;                 __builtin_amdgcn_wave_barrier();
;                 *(float4*)(blk + 4 * lane) = *(const float4*)(oq + 4 * lane);
;                 if (lane < 32) *(float4*)(blk + 256 + 4 * lane) = *(const float4*)(oq + 256 + 4 * lane);
.LBB0_797:
	s_or_b64 exec, exec, s[2:3]
	s_nop 0
	v_add_f32_e32 v134, v190, v138
	v_mul_f32_e32 v134, 0xbfb8aa3b, v134
	v_exp_f32_e32 v134, v134
	v_sub_f32_e32 v136, v167, v214
	v_fmac_f32_e32 v214, v191, v136
	v_add_f32_e32 v137, 1.0, v134
	v_div_scale_f32 v138, s[2:3], v137, v137, 1.0
	v_rcp_f32_e32 v154, v138
	v_pk_add_f32 v[134:135], v[142:143], v[144:145]
	v_div_scale_f32 v142, vcc, 1.0, v137, 1.0
	v_fma_f32 v143, -v138, v154, 1.0
	v_fmac_f32_e32 v154, v143, v154
	v_mul_f32_e32 v143, v142, v154
	v_fma_f32 v144, -v138, v143, v142
	v_fmac_f32_e32 v143, v144, v154
	v_fma_f32 v138, -v138, v143, v142
	v_div_fmas_f32 v138, v138, v154, v143
	v_div_fixup_f32 v137, v138, v137, 1.0
	v_mul_f32_e32 v137, 0xbf1b4598, v137
	v_mul_f32_e32 v137, 0x3fb8aa3b, v137
	v_exp_f32_e32 v142, v137
	v_mul_f32_e32 v136, v188, v134
	s_add_i32 s2, s23, 0xfffffaa2
	v_fma_f32 v143, v139, v142, -v136
	v_mul_f32_e32 v253, v188, v255
	v_mul_f32_e32 v254, v142, v255
	ds_write2st64_b32 v203, v253, v254 offset0:166 offset1:167
	v_mul_f32_e32 v253, v143, v255
	ds_write2st64_b32 v203, v253, v214 offset0:170 offset1:171
	v_cndmask_b32_e64 v255, v254, 1.0, s[98:99]
	v_rcp_f32_e32 v254, v255
	s_nop 0
	v_mul_f32_e32 v253, v217, v254
	v_mul_f32_e32 v254, v189, v254
	ds_write2st64_b32 v203, v253, v254 offset0:168 offset1:169
	ds_read_b128 v[142:145], v204
	v_mad_u64_u32 v[136:137], s[2:3], s2, 6, v[170:171]
	v_mov_b64_e32 v[138:139], s[18:19]
	v_mad_u64_u32 v[138:139], s[2:3], v136, s25, v[138:139]
	v_mad_u32_u24 v139, v137, s25, v139
	v_lshl_add_u64 v[136:137], v[138:139], 0, v[132:133]
	s_waitcnt lgkmcnt(0)
	global_store_dwordx4 v[136:137], v[142:145], off
	s_and_saveexec_b64 s[2:3], s[10:11]
	s_cbranch_execz .LBB0_799
	ds_read_b128 v[142:145], v205
	s_waitcnt lgkmcnt(0)
	global_store_dwordx4 v[136:137], v[142:145], off offset:1024

; __device__ __forceinline__ void p2_rwkv_prep(const Params& P, float* lds) {
;     ...
;             for (int tk = tg; tk < tg + 4; ++tk) {
;                 float* blk = RSB + ((size_t)(tok0 + tk) * RH + h) * RSB_BLK;
;                 float* oq = ot + (tk & 1) * 384;
;                 oq[cc] = ekk[tk - tg]; oq[64 + cc] = ew[tk - tg]; oq[128 + cc] = ebb[tk - tg]; oq[192 + cc] = ekm[tk - tg]; oq[256 + cc] = ewr[tk - tg]; oq[320 + cc] = ev[tk - tg];
;                 __builtin_amdgcn_wave_barrier();
;                 *(float4*)(blk + 4 * lane) = *(const float4*)(oq + 4 * lane);
;                 if (lane < 32) *(float4*)(blk + 256 + 4 * lane) = *(const float4*)(oq + 256 + 4 * lane);
.LBB0_801:
	s_or_b64 exec, exec, s[2:3]
	s_nop 0
	v_add_f32_e32 v134, v190, v140
	v_mul_f32_e32 v134, 0xbfb8aa3b, v134
	v_exp_f32_e32 v134, v134
	v_sub_f32_e32 v137, v218, v216
	v_fmac_f32_e32 v216, v191, v137
	v_add_f32_e32 v134, 1.0, v134
	v_div_scale_f32 v135, s[2:3], v134, v134, 1.0
	v_rcp_f32_e32 v136, v135
	v_div_scale_f32 v138, vcc, 1.0, v134, 1.0
	v_fma_f32 v139, -v135, v136, 1.0
	v_fmac_f32_e32 v136, v139, v136
	v_mul_f32_e32 v139, v138, v136
	v_fma_f32 v140, -v135, v139, v138
	v_fmac_f32_e32 v139, v140, v136
	v_fma_f32 v135, -v135, v139, v138
	v_div_fmas_f32 v135, v135, v136, v139
	v_div_fixup_f32 v134, v135, v134, 1.0
	v_mul_f32_e32 v134, 0xbf1b4598, v134
	v_mul_f32_e32 v134, 0x3fb8aa3b, v134
	v_exp_f32_e32 v140, v134
	v_pk_add_f32 v[134:135], v[146:147], v[148:149]
	v_mov_b64_e32 v[138:139], s[18:19]
	v_mul_f32_e32 v136, v186, v134
	v_fma_f32 v141, v141, v140, -v136
	v_mul_f32_e32 v253, v186, v255
	v_mul_f32_e32 v254, v140, v255
	ds_write2st64_b32 v200, v253, v254 offset0:160 offset1:161
	v_mul_f32_e32 v253, v141, v255
	ds_write2st64_b32 v200, v253, v216 offset0:164 offset1:165
	v_cndmask_b32_e64 v255, v254, 1.0, s[98:99]
	v_rcp_f32_e32 v254, v255
	s_nop 0
	v_mul_f32_e32 v253, v221, v254
	v_mul_f32_e32 v254, v187, v254
	ds_write2st64_b32 v200, v253, v254 offset0:162 offset1:163
	ds_read_b128 v[140:143], v201
	v_mad_u64_u32 v[136:137], s[2:3], s33, 6, v[170:171]
	v_mad_u64_u32 v[138:139], s[2:3], v136, s25, v[138:139]
	v_mad_u32_u24 v139, v137, s25, v139
	v_lshl_add_u64 v[136:137], v[138:139], 0, v[132:133]
	s_waitcnt lgkmcnt(0)
	global_store_dwordx4 v[136:137], v[140:143], off
	s_and_saveexec_b64 s[2:3], s[10:11]
	s_cbranch_execz .LBB0_803
	ds_read_b128 v[140:143], v202
	s_waitcnt lgkmcnt(0)
	global_store_dwordx4 v[136:137], v[140:143], off offset:1024

; __device__ __forceinline__ void p2_rwkv_prep(const Params& P, float* lds) {
;     ...
;             for (int tk = tg; tk < tg + 4; ++tk) {
;                 float* blk = RSB + ((size_t)(tok0 + tk) * RH + h) * RSB_BLK;
;                 float* oq = ot + (tk & 1) * 384;
;                 oq[cc] = ekk[tk - tg]; oq[64 + cc] = ew[tk - tg]; oq[128 + cc] = ebb[tk - tg]; oq[192 + cc] = ekm[tk - tg]; oq[256 + cc] = ewr[tk - tg]; oq[320 + cc] = ev[tk - tg];
;                 __builtin_amdgcn_wave_barrier();
;                 *(float4*)(blk + 4 * lane) = *(const float4*)(oq + 4 * lane);
;                 if (lane < 32) *(float4*)(blk + 256 + 4 * lane) = *(const float4*)(oq + 256 + 4 * lane);
.LBB0_805:
	s_or_b64 exec, exec, s[2:3]
	v_add_f32_e32 v130, v190, v130
	v_mul_f32_e32 v130, 0xbfb8aa3b, v130
	v_exp_f32_e32 v130, v130
	s_waitcnt vmcnt(6)
	v_sub_f32_e32 v136, v222, v215
	v_add_f32_e32 v130, 1.0, v130
	v_div_scale_f32 v134, s[2:3], v130, v130, 1.0
	v_rcp_f32_e32 v135, v134
	v_div_scale_f32 v137, vcc, 1.0, v130, 1.0
	v_fma_f32 v138, -v134, v135, 1.0
	v_fmac_f32_e32 v135, v138, v135
	v_mul_f32_e32 v138, v137, v135
	v_fma_f32 v139, -v134, v138, v137
	v_fmac_f32_e32 v138, v139, v135
	v_fma_f32 v134, -v134, v138, v137
	v_div_fmas_f32 v134, v134, v135, v138
	v_div_fixup_f32 v130, v134, v130, 1.0
	v_mul_f32_e32 v130, 0xbf1b4598, v130
	v_mul_f32_e32 v130, 0x3fb8aa3b, v130
	v_exp_f32_e32 v138, v130
	v_pk_add_f32 v[134:135], v[150:151], v[152:153]
	v_fma_f32 v139, v191, v136, v215
	v_mul_f32_e32 v130, v184, v134
	v_fma_f32 v140, v131, v138, -v130
	v_mul_f32_e32 v253, v184, v255
	v_mul_f32_e32 v254, v138, v255
	ds_write2st64_b32 v203, v253, v254 offset0:166 offset1:167
	v_mul_f32_e32 v253, v140, v255
	ds_write2st64_b32 v203, v253, v139 offset0:170 offset1:171
	v_cndmask_b32_e64 v255, v254, 1.0, s[98:99]
	v_rcp_f32_e32 v254, v255
	s_nop 0
	v_mul_f32_e32 v253, v225, v254
	v_mul_f32_e32 v254, v185, v254
	ds_write2st64_b32 v203, v253, v254 offset0:168 offset1:169
	ds_read_b128 v[138:141], v204
	v_mad_u64_u32 v[136:137], s[2:3], s34, 6, v[170:171]
	v_mov_b64_e32 v[130:131], s[18:19]
	v_mad_u64_u32 v[130:131], s[2:3], v136, s25, v[130:131]
	v_mad_u32_u24 v131, v137, s25, v131
	v_lshl_add_u64 v[136:137], v[130:131], 0, v[132:133]
	s_waitcnt lgkmcnt(0)
	global_store_dwordx4 v[136:137], v[138:141], off
	s_and_saveexec_b64 s[2:3], s[10:11]
	s_cbranch_execz .LBB0_807
	ds_read_b128 v[138:141], v205
	s_waitcnt lgkmcnt(0)
	global_store_dwordx4 v[136:137], v[138:141], off offset:1024

; __device__ __forceinline__ float bf2f(bf16_t b) { return __uint_as_float(((unsigned)b) << 16); }
; __device__ __forceinline__ float sigmoidf_(float x) { return 1.f / (1.f + __expf(-x)); }
; __device__ __forceinline__ void p2_rwkv_prep(const Params& P, float* lds) {
;     ...
;             for (int tk = tg; tk < tg + 4; ++tk) {
;                 const int tok = tok0 + tk;
;                 if (tok >= NTOK) { const float* p = P.state_shift + (size_t)(tok - NTOK) * RCOLS + tid; qr = p[0]; qk = p[RW]; qv = p[2 * RW]; }
;                 const float cr = nr[tk & 3], ck = nk[tk & 3], cv = nv[tk & 3];
;                 if (tk + 4 < CT) { const bf16_t* p = prw + (size_t)(tok + 4) * RCOLS + tid; nr[tk & 3] = bf2f(p[0]); nk[tk & 3] = bf2f(p[RW]); nv[tk & 3] = bf2f(p[2 * RW]); }
;                 const float r = cr + (qr - cr) * mur, kraw = ck + (qk - ck) * muk, v = cv + (qv - cv) * muv;
;                 qr = cr; qk = ck; qv = cv;
;                 const float aw = w0c + yt[tk * 64 + cc], aa = a0c + yt[(CT + tk) * 64 + cc];
;                 const float w = __expf(-DECAY_SCALE * sigmoidf_(aw)), a = sigmoidf_(aa);
;                 const float kkv = kraw * kkc;
;                 const float n2 = wave_sum_fast(kkv * kkv);
;                 const float kk = kkv * rsqrtf(fmaxf(n2, 1e-12f));
;                 const float kmod = kraw * (1.f + (a - 1.f) * kac);
;                 const float bb = kk * a;
;                 const float br = wave_sum_fast(bb * r);
;                 ekk[tk - tg] = kk; ew[tk - tg] = w; ebb[tk - tg] = bb; ekm[tk - tg] = kmod; ewr[tk - tg] = w * r - kk * br; ev[tk - tg] = v;
;                 ebr[tk - tg] = br; ekr[tk - tg] = wave_sum_fast(kmod * r); erk[tk - tg] = wave_sum_fast(r * kmod * rkc);
;             }
; #pragma unroll
;             for (int tk = tg; tk < tg + 4; ++tk) {
;                 float* blk = RSB + ((size_t)(tok0 + tk) * RH + h) * RSB_BLK;
;                 float* oq = ot + (tk & 1) * 384;
;                 oq[cc] = ekk[tk - tg]; oq[64 + cc] = ew[tk - tg]; oq[128 + cc] = ebb[tk - tg]; oq[192 + cc] = ekm[tk - tg]; oq[256 + cc] = ewr[tk - tg]; oq[320 + cc] = ev[tk - tg];
;                 __builtin_amdgcn_wave_barrier();
;                 *(float4*)(blk + 4 * lane) = *(const float4*)(oq + 4 * lane);
;                 if (lane < 32) *(float4*)(blk + 256 + 4 * lane) = *(const float4*)(oq + 256 + 4 * lane);
.LBB0_817:
	v_add_f32_e32 v134, v190, v134
	v_mul_f32_e32 v134, 0xbfb8aa3b, v134
	v_exp_f32_e32 v134, v134
	s_waitcnt vmcnt(0)
	v_sub_f32_e32 v182, v215, v213
	ds_read2st64_b32 v[150:151], v199 offset0:39 offset1:47
	v_fma_f32 v224, v191, v182, v213
	v_add_f32_e32 v134, 1.0, v134
	v_div_scale_f32 v135, s[2:3], v134, v134, 1.0
	v_rcp_f32_e32 v183, v135
	v_div_scale_f32 v215, vcc, 1.0, v134, 1.0
	v_lshlrev_b32_e32 v182, 16, v165
	v_fma_f32 v222, -v135, v183, 1.0
	v_fmac_f32_e32 v183, v222, v183
	v_mul_f32_e32 v222, v215, v183
	v_fma_f32 v223, -v135, v222, v215
	v_fmac_f32_e32 v222, v223, v183
	v_fma_f32 v135, -v135, v222, v215
	v_div_fmas_f32 v135, v135, v183, v222
	v_div_fixup_f32 v134, v135, v134, 1.0
	v_mul_f32_e32 v134, 0xbf1b4598, v134
	v_mul_f32_e32 v134, 0x3fb8aa3b, v134
	v_exp_f32_e32 v215, v134
	v_pk_add_f32 v[134:135], v[136:137], v[148:149]
	v_lshlrev_b32_e32 v183, 16, v166
	v_mul_f32_e32 v136, v154, v134
	v_fma_f32 v225, v152, v215, -v136
	s_waitcnt lgkmcnt(0)
	v_add_f32_e32 v136, v194, v151
	v_mul_f32_e32 v136, 0xbfb8aa3b, v136
	v_exp_f32_e32 v136, v136
	v_sub_f32_e32 v137, v221, v182
	v_fma_f32 v151, v196, v137, v182
	v_sub_f32_e32 v137, v153, v183
	v_add_f32_e32 v136, 1.0, v136
	v_div_scale_f32 v148, s[2:3], v136, v136, 1.0
	v_rcp_f32_e32 v149, v148
	v_fma_f32 v137, v195, v137, v183
	s_mul_hi_u32 s31, s16, 6
	s_mul_i32 s16, s16, 6
	v_fma_f32 v152, -v148, v149, 1.0
	v_fmac_f32_e32 v149, v152, v149
	v_div_scale_f32 v152, vcc, 1.0, v136, 1.0
	v_mul_f32_e32 v153, v152, v149
	v_fma_f32 v165, -v148, v153, v152
	v_fmac_f32_e32 v153, v165, v149
	v_fma_f32 v148, -v148, v153, v152
	v_mul_f32_e32 v152, v193, v137
	v_mul_f32_e32 v165, v152, v152
	v_div_fmas_f32 v148, v148, v149, v153
	v_div_fixup_f32 v136, v148, v136, 1.0
	v_mov_b32_dpp v165, v165 quad_perm:[1,0,3,2] row_mask:0xf bank_mask:0xf bound_ctrl:1
	v_fmac_f32_e32 v165, v152, v152
	v_add_f32_e32 v148, -1.0, v136
	v_fma_f32 v148, v192, v148, 1.0
	v_add_f32_dpp v165, v165, v165 quad_perm:[2,3,0,1] row_mask:0xf bank_mask:0xf bound_ctrl:1
	v_mul_f32_e32 v253, v154, v255
	v_mul_f32_e32 v254, v215, v255
	ds_write2st64_b32 v200, v253, v254 offset0:160 offset1:161
	v_mul_f32_e32 v253, v225, v255
	ds_write2st64_b32 v200, v253, v224 offset0:164 offset1:165
	v_cndmask_b32_e64 v255, v254, 1.0, s[98:99]
	v_rcp_f32_e32 v254, v255
	s_nop 0
	v_mul_f32_e32 v253, v156, v254
	v_mul_f32_e32 v254, v155, v254
	ds_write2st64_b32 v200, v253, v254 offset0:162 offset1:163
	v_add_f32_dpp v165, v165, v165 row_ror:4 row_mask:0xf bank_mask:0xf bound_ctrl:1
	ds_read_b128 v[224:227], v201
	v_or_b32_e32 v228, s16, v170
	v_add_f32_dpp v165, v165, v165 row_ror:8 row_mask:0xf bank_mask:0xf bound_ctrl:1
	v_mov_b32_e32 v166, v165
	s_nop 1
	v_permlane16_swap_b32_e32 v165, v166
	v_add_f32_e32 v165, v165, v166
	v_mov_b32_e32 v166, v165
	s_nop 1
	v_permlane32_swap_b32_e32 v165, v166
	v_add_f32_e32 v165, v165, v166
	v_max_f32_e32 v165, 0x2b8cbccc, v165
	v_rsq_f32_e32 v165, v165
	v_mul_f32_e32 v166, v137, v148
	v_mul_f32_e32 v165, v152, v165
	v_mul_f32_e32 v221, v136, v165
	v_mul_f32_e32 v136, v151, v221
	s_nop 1
	v_mov_b32_dpp v136, v136 quad_perm:[1,0,3,2] row_mask:0xf bank_mask:0xf bound_ctrl:1
	v_fmac_f32_e32 v136, v151, v221
	s_nop 1
	v_add_f32_dpp v136, v136, v136 quad_perm:[2,3,0,1] row_mask:0xf bank_mask:0xf bound_ctrl:1
	s_nop 1
	v_add_f32_dpp v136, v136, v136 row_ror:4 row_mask:0xf bank_mask:0xf bound_ctrl:1
	s_nop 1
	v_add_f32_dpp v136, v136, v136 row_ror:8 row_mask:0xf bank_mask:0xf bound_ctrl:1
	v_mov_b32_e32 v137, v136
	s_nop 1
	v_permlane16_swap_b32_e32 v136, v137
	v_add_f32_e32 v148, v136, v137
	v_mul_f32_e32 v136, v151, v166
	v_mov_b32_e32 v152, v148
	s_nop 1
	v_permlane32_swap_b32_e32 v148, v152
	v_mov_b32_dpp v137, v136 quad_perm:[1,0,3,2] row_mask:0xf bank_mask:0xf bound_ctrl:1
	v_fmac_f32_e32 v137, v151, v166
	s_nop 1
	v_add_f32_dpp v137, v137, v137 quad_perm:[2,3,0,1] row_mask:0xf bank_mask:0xf bound_ctrl:1
	s_nop 1
	v_add_f32_dpp v137, v137, v137 row_ror:4 row_mask:0xf bank_mask:0xf bound_ctrl:1
	s_nop 1
	v_add_f32_dpp v137, v137, v137 row_ror:8 row_mask:0xf bank_mask:0xf bound_ctrl:1
	v_mov_b32_e32 v149, v137
	s_nop 1
	v_permlane16_swap_b32_e32 v137, v149
	v_add_f32_e32 v149, v137, v149
	v_mul_f32_e32 v137, v197, v136
	v_mov_b32_e32 v153, v149
	s_nop 1
	v_permlane32_swap_b32_e32 v149, v153
	v_mov_b32_dpp v137, v137 quad_perm:[1,0,3,2] row_mask:0xf bank_mask:0xf bound_ctrl:1
	v_fmac_f32_e32 v137, v197, v136
	s_nop 1
	v_add_f32_dpp v136, v137, v137 quad_perm:[2,3,0,1] row_mask:0xf bank_mask:0xf bound_ctrl:1
	s_nop 1
	v_add_f32_dpp v136, v136, v136 row_ror:4 row_mask:0xf bank_mask:0xf bound_ctrl:1
	s_nop 1
	v_add_f32_dpp v136, v136, v136 row_ror:8 row_mask:0xf bank_mask:0xf bound_ctrl:1
	v_mov_b32_e32 v137, v136
	s_nop 1
	v_permlane16_swap_b32_e32 v136, v137
	v_add_f32_e32 v222, v136, v137
	v_mov_b64_e32 v[136:137], s[18:19]
	v_mad_u64_u32 v[154:155], s[2:3], v228, s25, v[136:137]
	v_mov_b32_e32 v223, v222
	v_mad_u32_u24 v155, s31, v211, v155
	s_nop 0
	v_permlane32_swap_b32_e32 v222, v223
	v_lshl_add_u64 v[136:137], v[154:155], 0, v[132:133]
	s_waitcnt lgkmcnt(0)
	global_store_dwordx4 v[136:137], v[224:227], off
	s_and_saveexec_b64 s[2:3], s[10:11]
	s_cbranch_execz .LBB0_819
	ds_read_b128 v[224:227], v202
	s_waitcnt lgkmcnt(0)
	global_store_dwordx4 v[136:137], v[224:227], off offset:1024

; __device__ __forceinline__ void p2_rwkv_prep(const Params& P, float* lds) {
;     ...
;             for (int tk = tg; tk < tg + 4; ++tk) {
;                 float* blk = RSB + ((size_t)(tok0 + tk) * RH + h) * RSB_BLK;
;                 float* oq = ot + (tk & 1) * 384;
;                 oq[cc] = ekk[tk - tg]; oq[64 + cc] = ew[tk - tg]; oq[128 + cc] = ebb[tk - tg]; oq[192 + cc] = ekm[tk - tg]; oq[256 + cc] = ewr[tk - tg]; oq[320 + cc] = ev[tk - tg];
;                 __builtin_amdgcn_wave_barrier();
;                 *(float4*)(blk + 4 * lane) = *(const float4*)(oq + 4 * lane);
;                 if (lane < 32) *(float4*)(blk + 256 + 4 * lane) = *(const float4*)(oq + 256 + 4 * lane);
.LBB0_821:
	s_or_b64 exec, exec, s[2:3]
	v_add_f32_e32 v130, v190, v130
	v_mul_f32_e32 v130, 0xbfb8aa3b, v130
	v_exp_f32_e32 v130, v130
	v_sub_f32_e32 v136, v157, v214
	v_add_f32_e32 v130, 1.0, v130
	v_div_scale_f32 v134, s[2:3], v130, v130, 1.0
	v_rcp_f32_e32 v135, v134
	v_div_scale_f32 v137, vcc, 1.0, v130, 1.0
	v_fma_f32 v154, -v134, v135, 1.0
	v_fmac_f32_e32 v135, v154, v135
	v_mul_f32_e32 v154, v137, v135
	v_fma_f32 v155, -v134, v154, v137
	v_fmac_f32_e32 v154, v155, v135
	v_fma_f32 v134, -v134, v154, v137
	v_div_fmas_f32 v134, v134, v135, v154
	v_div_fixup_f32 v130, v134, v130, 1.0
	v_mul_f32_e32 v130, 0xbf1b4598, v130
	v_mul_f32_e32 v130, 0x3fb8aa3b, v130
	v_exp_f32_e32 v154, v130
	v_pk_add_f32 v[134:135], v[138:139], v[140:141]
	v_fma_f32 v138, v191, v136, v214
	v_mul_f32_e32 v130, v159, v134
	v_fma_f32 v139, v131, v154, -v130
	v_mul_f32_e32 v253, v159, v255
	v_mul_f32_e32 v254, v154, v255
	ds_write2st64_b32 v203, v253, v254 offset0:166 offset1:167
	v_mul_f32_e32 v253, v139, v255
	ds_write2st64_b32 v203, v253, v138 offset0:170 offset1:171
	v_cndmask_b32_e64 v255, v254, 1.0, s[98:99]
	v_rcp_f32_e32 v254, v255
	s_nop 0
	v_mul_f32_e32 v253, v161, v254
	v_mul_f32_e32 v254, v160, v254
	ds_write2st64_b32 v203, v253, v254 offset0:168 offset1:169
	ds_read_b128 v[138:141], v204
	v_mad_u64_u32 v[136:137], s[2:3], s17, 6, v[170:171]
	v_mov_b64_e32 v[130:131], s[18:19]
	v_mad_u64_u32 v[130:131], s[2:3], v136, s25, v[130:131]
	v_mad_u32_u24 v131, v137, s25, v131
	v_lshl_add_u64 v[136:137], v[130:131], 0, v[132:133]
	s_waitcnt lgkmcnt(0)
	global_store_dwordx4 v[136:137], v[138:141], off
	s_and_saveexec_b64 s[2:3], s[10:11]
	s_cbranch_execz .LBB0_823
	ds_read_b128 v[138:141], v205
	s_waitcnt lgkmcnt(0)
	global_store_dwordx4 v[136:137], v[138:141], off offset:1024

; __device__ __forceinline__ void p2_rwkv_prep(const Params& P, float* lds) {
;     ...
;             for (int tk = tg; tk < tg + 4; ++tk) {
;                 float* blk = RSB + ((size_t)(tok0 + tk) * RH + h) * RSB_BLK;
;                 float* oq = ot + (tk & 1) * 384;
;                 oq[cc] = ekk[tk - tg]; oq[64 + cc] = ew[tk - tg]; oq[128 + cc] = ebb[tk - tg]; oq[192 + cc] = ekm[tk - tg]; oq[256 + cc] = ewr[tk - tg]; oq[320 + cc] = ev[tk - tg];
;                 __builtin_amdgcn_wave_barrier();
;                 *(float4*)(blk + 4 * lane) = *(const float4*)(oq + 4 * lane);
;                 if (lane < 32) *(float4*)(blk + 256 + 4 * lane) = *(const float4*)(oq + 256 + 4 * lane);
.LBB0_825:
	s_or_b64 exec, exec, s[2:3]
	v_add_f32_e32 v130, v190, v142
	v_mul_f32_e32 v130, 0xbfb8aa3b, v130
	v_exp_f32_e32 v130, v130
	v_sub_f32_e32 v136, v168, v216
	v_fma_f32 v139, v191, v136, v216
	v_add_f32_e32 v130, 1.0, v130
	v_div_scale_f32 v131, s[2:3], v130, v130, 1.0
	v_rcp_f32_e32 v134, v131
	v_div_scale_f32 v135, vcc, 1.0, v130, 1.0
	v_fma_f32 v137, -v131, v134, 1.0
	v_fmac_f32_e32 v134, v137, v134
	v_mul_f32_e32 v137, v135, v134
	v_fma_f32 v138, -v131, v137, v135
	v_fmac_f32_e32 v137, v138, v134
	v_fma_f32 v131, -v131, v137, v135
	v_div_fmas_f32 v131, v131, v134, v137
	v_div_fixup_f32 v130, v131, v130, 1.0
	v_mul_f32_e32 v130, 0xbf1b4598, v130
	v_mul_f32_e32 v130, 0x3fb8aa3b, v130
	v_exp_f32_e32 v138, v130
	v_pk_add_f32 v[134:135], v[144:145], v[146:147]
	v_mad_u64_u32 v[136:137], s[2:3], s20, 6, v[170:171]
	v_mul_f32_e32 v130, v163, v134
	v_fma_f32 v140, v143, v138, -v130
	v_mul_f32_e32 v253, v163, v255
	v_mul_f32_e32 v254, v138, v255
	ds_write2st64_b32 v200, v253, v254 offset0:160 offset1:161
	v_mul_f32_e32 v253, v140, v255
	ds_write2st64_b32 v200, v253, v139 offset0:164 offset1:165
	v_cndmask_b32_e64 v255, v254, 1.0, s[98:99]
	v_rcp_f32_e32 v254, v255
	s_nop 0
	v_mul_f32_e32 v253, v218, v254
	v_mul_f32_e32 v254, v164, v254
	ds_write2st64_b32 v200, v253, v254 offset0:162 offset1:163
	ds_read_b128 v[138:141], v201
	v_mov_b64_e32 v[130:131], s[18:19]
	v_mad_u64_u32 v[130:131], s[2:3], v136, s25, v[130:131]
	v_mad_u32_u24 v131, v137, s25, v131
	v_lshl_add_u64 v[136:137], v[130:131], 0, v[132:133]
	s_waitcnt lgkmcnt(0)
	global_store_dwordx4 v[136:137], v[138:141], off
	s_and_saveexec_b64 s[2:3], s[10:11]
	s_cbranch_execz .LBB0_827
	ds_read_b128 v[138:141], v202
	s_waitcnt lgkmcnt(0)
	global_store_dwordx4 v[136:137], v[138:141], off offset:1024

; __device__ __forceinline__ void p2_rwkv_prep(const Params& P, float* lds) {
;     ...
;             for (int tk = tg; tk < tg + 4; ++tk) {
;                 float* blk = RSB + ((size_t)(tok0 + tk) * RH + h) * RSB_BLK;
;                 float* oq = ot + (tk & 1) * 384;
;                 oq[cc] = ekk[tk - tg]; oq[64 + cc] = ew[tk - tg]; oq[128 + cc] = ebb[tk - tg]; oq[192 + cc] = ekm[tk - tg]; oq[256 + cc] = ewr[tk - tg]; oq[320 + cc] = ev[tk - tg];
;                 __builtin_amdgcn_wave_barrier();
;                 *(float4*)(blk + 4 * lane) = *(const float4*)(oq + 4 * lane);
;                 if (lane < 32) *(float4*)(blk + 256 + 4 * lane) = *(const float4*)(oq + 256 + 4 * lane);
.LBB0_829:
	s_or_b64 exec, exec, s[2:3]
	v_add_f32_e32 v130, v190, v150
	v_mul_f32_e32 v130, 0xbfb8aa3b, v130
	v_exp_f32_e32 v130, v130
	v_lshlrev_b32_e32 v215, 16, v1
	v_add_f32_e32 v1, 1.0, v130
	v_div_scale_f32 v134, s[2:3], v1, v1, 1.0
	v_rcp_f32_e32 v135, v134
	v_div_scale_f32 v136, vcc, 1.0, v1, 1.0
	v_pk_add_f32 v[130:131], v[148:149], v[152:153]
	v_fma_f32 v137, -v134, v135, 1.0
	v_fmac_f32_e32 v135, v137, v135
	v_mul_f32_e32 v137, v136, v135
	v_fma_f32 v138, -v134, v137, v136
	v_fmac_f32_e32 v137, v138, v135
	v_fma_f32 v134, -v134, v137, v136
	v_div_fmas_f32 v134, v134, v135, v137
	v_div_fixup_f32 v1, v134, v1, 1.0
	v_mul_f32_e32 v1, 0xbf1b4598, v1
	v_mul_f32_e32 v1, 0x3fb8aa3b, v1
	v_exp_f32_e32 v1, v1
	v_sub_f32_e32 v134, v162, v215
	v_mul_f32_e32 v135, v165, v130
	v_fma_f32 v138, v191, v134, v215
	v_fma_f32 v139, v151, v1, -v135
	v_mul_f32_e32 v253, v165, v255
	v_mul_f32_e32 v254, v1, v255
	ds_write2st64_b32 v203, v253, v254 offset0:166 offset1:167
	v_mul_f32_e32 v253, v139, v255
	ds_write2st64_b32 v203, v253, v138 offset0:170 offset1:171
	v_cndmask_b32_e64 v255, v254, 1.0, s[98:99]
	v_rcp_f32_e32 v254, v255
	s_nop 0
	v_mul_f32_e32 v253, v221, v254
	v_mul_f32_e32 v254, v166, v254
	ds_write2st64_b32 v203, v253, v254 offset0:168 offset1:169
	ds_read_b128 v[138:141], v204
	v_mad_u64_u32 v[136:137], s[2:3], s21, 6, v[170:171]
	v_mov_b64_e32 v[134:135], s[18:19]
	v_mad_u64_u32 v[134:135], s[2:3], v136, s25, v[134:135]
	v_mad_u32_u24 v135, v137, s25, v135
	v_lshl_add_u64 v[136:137], v[134:135], 0, v[132:133]
	s_waitcnt lgkmcnt(0)
	global_store_dwordx4 v[136:137], v[138:141], off
	s_and_saveexec_b64 s[2:3], s[10:11]
	s_cbranch_execz .LBB0_831
	ds_read_b128 v[138:141], v205
	s_waitcnt lgkmcnt(0)
	global_store_dwordx4 v[136:137], v[138:141], off offset:1024

; __device__ __forceinline__ float scan_step_asm(float4& S, const StepIn& s) {
;     float o, d1, d2, t;
;     asm volatile(
;         "v_mul_f32 %5, %0, %8\n\t"  "v_mul_f32 %6, %0, %12\n\t"
;         "v_fmac_f32 %5, %1, %9\n\t" "v_fmac_f32 %6, %1, %13\n\t"
;         "v_fmac_f32 %5, %2, %10\n\t" "v_fmac_f32 %6, %2, %14\n\t"
;         "v_fmac_f32 %5, %3, %11\n\t" "v_fmac_f32 %6, %3, %15\n\t"
;         "v_mul_f32 %0, %0, %16\n\t" "v_mul_f32 %1, %1, %17\n\t"
;         "v_add_f32_dpp %5, %5, %5 quad_perm:[1,0,3,2] row_mask:0xf bank_mask:0xf\n\t"
;         "v_add_f32_dpp %6, %6, %6 quad_perm:[1,0,3,2] row_mask:0xf bank_mask:0xf\n\t"
;         "v_mul_f32 %2, %2, %18\n\t" "v_mul_f32 %3, %3, %19\n\t"
;         "v_add_f32_dpp %5, %5, %5 quad_perm:[2,3,0,1] row_mask:0xf bank_mask:0xf\n\t"
;         "v_add_f32_dpp %6, %6, %6 quad_perm:[2,3,0,1] row_mask:0xf bank_mask:0xf\n\t"
;         "v_fmac_f32 %0, %28, %20\n\t" "v_fmac_f32 %1, %28, %21\n\t"
; __device__ __forceinline__ void scan_prompt_wave(const Params& P, unsigned char* lds, int b, int h, int quarter) {
;     ...
;         const int rl = quarter * 16 + wave * 4 + (lane >> 4), cl = lane & 15, c0 = cl * 4;
;         float* op = (float*)(P.ws + WS_ORAW) + (size_t)(b * SEQ) * RW + h * 64 + rl;
;         float4 S = make_float4(0.f, 0.f, 0.f, 0.f);
;         while (scw[0] < 1u) __builtin_amdgcn_s_sleep(1);
;         asm volatile("" ::: "memory");
;         StepIn r[4];
;         lds_load_step(r[0], (const float*)lds, c0, rl); lds_load_step(r[1], (const float*)lds + RSB_BLK, c0, rl); lds_load_step(r[2], (const float*)lds + 2 * RSB_BLK, c0, rl);
;         for (int c = 0; c < NCH; ++c) {
;             const float* bp = (const float*)(lds + (c % SC_NB) * SC_BUF); const float* bpn = (const float*)(lds + ((c + 1) % SC_NB) * SC_BUF);
;             float ov = 0.f;
; #pragma unroll
;             for (int s = 0; s < SCH; ++s) {
;                 if (s == SCH - 3 && c + 1 < NCH) { while (scw[0] < (unsigned)(c + 2)) __builtin_amdgcn_s_sleep(1); asm volatile("" ::: "memory"); }
;                 lds_load_step(r[(s + 3) & 3], (s + 3 < SCH) ? bp + (s + 3) * RSB_BLK : bpn + (s + 3 - SCH) * RSB_BLK, c0, rl); __builtin_amdgcn_sched_barrier(0);
;                 const float o = scan_step_asm(S, r[s & 3]); __builtin_amdgcn_sched_barrier(0);
;                 ov = (cl == s) ? o : ov;
;             }
;             op[(size_t)cl * RW] = ov;
.LBB0_1226:
	s_lshr_b32 s0, s56, 3
	s_and_b32 s0, s0, 3
	s_lshl_b32 s0, s0, 4
	s_lshl_b32 s3, s2, 2
	s_or_b32 s0, s3, s0
	v_lshrrev_b32_e32 v2, 4, v1
	v_or_b32_e32 v2, s0, v2
	v_lshlrev_b32_e32 v115, 2, v2
	v_and_b32_e32 v3, 15, v1
	v_lshlrev_b32_e32 v114, 4, v3
	v_and_b32_e32 v121, 3, v1
	v_bfe_u32 v124, v1, 2, 2
	v_lshl_add_u32 v124, v121, 2, v124
	v_mul_u32_u24_e32 v117, 0x610, v124
	v_add_u32_e32 v116, v117, v115
	v_cmp_eq_u32_e64 s[8:9], 1, v121
	v_cmp_eq_u32_e64 s[10:11], 2, v121
	v_cmp_eq_u32_e64 s[12:13], 3, v121
	s_mul_i32 s14, s33, 0x600000
	s_add_u32 s14, s78, s14
	s_addc_u32 s15, s79, 0
	s_lshl_b32 s16, s40, 8
	s_add_u32 s14, s14, s16
	s_addc_u32 s15, s15, 0
	s_add_u32 s14, s14, 0x1349cc00
	s_addc_u32 s15, s15, 0
	v_mul_u32_u24_e32 v124, 0x600, v124
	v_add_u32_e32 v124, v124, v115
	v_mov_b32_e32 v125, 0
	v_lshl_add_u64 v[122:123], s[14:15], 0, v[124:125]
	v_mov_b32_e32 v118, s41
	s_lshl_b32 s16, s2, 2
	s_add_i32 s16, s16, 0x23004
	v_mov_b32_e32 v119, s16
	s_mov_b32 s4, 0
	s_movk_i32 s5, 0x7000
	s_mov_b32 s42, 0
	s_mov_b32 s6, 2
	s_mov_b64 s[0:1], 0x6000
	v_mov_b32_e32 v4, 0
	v_mov_b32_e32 v5, 0
	v_mov_b32_e32 v6, 0
	v_mov_b32_e32 v7, 0
	v_mov_b32_e32 v110, v114
	v_mov_b32_e32 v111, v115
	v_add_u32_e32 v112, s5, v114
	v_add_u32_e32 v113, s5, v115
	ds_read_b128 v[8:11], v110
	ds_read_b128 v[24:27], v110 offset:1024
	ds_read_b32 v28, v111 offset:1280
	ds_read_b128 v[20:23], v110 offset:768
	ds_read_b128 v[16:19], v110 offset:512
	ds_read_b128 v[30:33], v110 offset:1552
	ds_read_b128 v[46:49], v110 offset:2576
	ds_read_b32 v50, v111 offset:2832
	ds_read_b128 v[42:45], v110 offset:2320
	ds_read_b128 v[38:41], v110 offset:2064
	ds_read_b128 v[52:55], v110 offset:3104
	ds_read_b128 v[68:71], v110 offset:4128
	ds_read_b32 v72, v111 offset:4384
	ds_read_b128 v[64:67], v110 offset:3872
	ds_read_b128 v[60:63], v110 offset:3616
.Lscan_chunk:
	s_waitcnt lgkmcnt(5)
	ds_read_b128 v[74:77], v110 offset:4656
	ds_read_b128 v[90:93], v110 offset:5680
	ds_read_b32 v94, v111 offset:5936
	ds_read_b128 v[86:89], v110 offset:5424
	ds_read_b128 v[82:85], v110 offset:5168
	v_mul_f32_e32 v108, v4, v8
	v_fmac_f32_e32 v108, v5, v9
	v_fmac_f32_e32 v108, v6, v10
	v_fmac_f32_e32 v108, v7, v11
	v_mul_f32_e32 v96, v4, v24
	v_fmac_f32_e32 v96, v5, v25
	v_add_f32_dpp v108, v108, v108 quad_perm:[1,0,3,2] row_mask:0xf bank_mask:0xf
	v_fmac_f32_e32 v96, v6, v26
	v_fmac_f32_e32 v96, v7, v27
	v_add_f32_dpp v108, v108, v108 quad_perm:[2,3,0,1] row_mask:0xf bank_mask:0xf
	v_fmac_f32_e32 v4, v28, v20
	v_fmac_f32_e32 v5, v28, v21
	v_add_f32_dpp v108, v108, v108 row_ror:4 row_mask:0xf bank_mask:0xf
	v_fmac_f32_e32 v6, v28, v22
	v_fmac_f32_e32 v7, v28, v23
	v_add_f32_dpp v108, v108, v108 row_ror:8 row_mask:0xf bank_mask:0xf
	v_fma_f32 v4, -v108, v16, v4
	v_fma_f32 v5, -v108, v17, v5
	v_fma_f32 v6, -v108, v18, v6
	v_fma_f32 v7, -v108, v19, v7
	ds_read_b128 v[8:11], v110 offset:6208
	ds_read_b128 v[24:27], v110 offset:7232
	ds_read_b32 v28, v111 offset:7488
	ds_read_b128 v[20:23], v110 offset:6976
	ds_read_b128 v[16:19], v110 offset:6720
	v_mul_f32_e32 v108, v4, v30
	v_fmac_f32_e32 v108, v5, v31
	v_fmac_f32_e32 v108, v6, v32
	v_fmac_f32_e32 v108, v7, v33
	v_mul_f32_e32 v97, v4, v46
	v_fmac_f32_e32 v97, v5, v47
	v_add_f32_dpp v108, v108, v108 quad_perm:[1,0,3,2] row_mask:0xf bank_mask:0xf
	v_fmac_f32_e32 v97, v6, v48
	v_fmac_f32_e32 v97, v7, v49
	v_add_f32_dpp v108, v108, v108 quad_perm:[2,3,0,1] row_mask:0xf bank_mask:0xf
	v_fmac_f32_e32 v4, v50, v42
	v_fmac_f32_e32 v5, v50, v43
	v_add_f32_dpp v108, v108, v108 row_ror:4 row_mask:0xf bank_mask:0xf
	v_fmac_f32_e32 v6, v50, v44
	v_fmac_f32_e32 v7, v50, v45
	v_add_f32_dpp v108, v108, v108 row_ror:8 row_mask:0xf bank_mask:0xf
	v_fma_f32 v4, -v108, v38, v4
	v_fma_f32 v5, -v108, v39, v5
	v_fma_f32 v6, -v108, v40, v6
	v_fma_f32 v7, -v108, v41, v7
	s_waitcnt lgkmcnt(5)
	ds_read_b128 v[30:33], v110 offset:7760
	ds_read_b128 v[46:49], v110 offset:8784
	ds_read_b32 v50, v111 offset:9040
	ds_read_b128 v[42:45], v110 offset:8528
	ds_read_b128 v[38:41], v110 offset:8272
	v_mul_f32_e32 v108, v4, v52
	v_fmac_f32_e32 v108, v5, v53
	v_fmac_f32_e32 v108, v6, v54
	v_fmac_f32_e32 v108, v7, v55
	v_mul_f32_e32 v98, v4, v68
	v_fmac_f32_e32 v98, v5, v69
	v_add_f32_dpp v108, v108, v108 quad_perm:[1,0,3,2] row_mask:0xf bank_mask:0xf
	v_fmac_f32_e32 v98, v6, v70
	v_fmac_f32_e32 v98, v7, v71
	v_add_f32_dpp v108, v108, v108 quad_perm:[2,3,0,1] row_mask:0xf bank_mask:0xf
	v_fmac_f32_e32 v4, v72, v64
	v_fmac_f32_e32 v5, v72, v65
	v_add_f32_dpp v108, v108, v108 row_ror:4 row_mask:0xf bank_mask:0xf
	v_fmac_f32_e32 v6, v72, v66
	v_fmac_f32_e32 v7, v72, v67
	v_add_f32_dpp v108, v108, v108 row_ror:8 row_mask:0xf bank_mask:0xf
	v_fma_f32 v4, -v108, v60, v4
	v_fma_f32 v5, -v108, v61, v5
	v_fma_f32 v6, -v108, v62, v6
	v_fma_f32 v7, -v108, v63, v7
	ds_read_b128 v[52:55], v110 offset:9312
	ds_read_b128 v[68:71], v110 offset:10336
	ds_read_b32 v72, v111 offset:10592
	ds_read_b128 v[64:67], v110 offset:10080
	ds_read_b128 v[60:63], v110 offset:9824
	v_mul_f32_e32 v108, v4, v74
	v_fmac_f32_e32 v108, v5, v75
	v_fmac_f32_e32 v108, v6, v76
	v_fmac_f32_e32 v108, v7, v77
	v_mul_f32_e32 v99, v4, v90
	v_fmac_f32_e32 v99, v5, v91
	v_add_f32_dpp v108, v108, v108 quad_perm:[1,0,3,2] row_mask:0xf bank_mask:0xf
	v_fmac_f32_e32 v99, v6, v92
	v_fmac_f32_e32 v99, v7, v93
	v_add_f32_dpp v108, v108, v108 quad_perm:[2,3,0,1] row_mask:0xf bank_mask:0xf
	v_add_f32_dpp v100, v96, v96 row_ror:8 row_mask:0xf bank_mask:0x3
	v_add_f32_dpp v100, v98, v98 row_ror:8 row_mask:0xf bank_mask:0xc
	v_add_f32_dpp v108, v108, v108 row_ror:4 row_mask:0xf bank_mask:0xf
	v_add_f32_dpp v101, v97, v97 row_ror:8 row_mask:0xf bank_mask:0x3
	v_add_f32_dpp v101, v99, v99 row_ror:8 row_mask:0xf bank_mask:0xc
	v_add_f32_dpp v108, v108, v108 row_ror:8 row_mask:0xf bank_mask:0xf
	v_fmac_f32_e32 v4, v94, v86
	v_fmac_f32_e32 v5, v94, v87
	v_add_f32_dpp v102, v100, v100 row_half_mirror row_mask:0xf bank_mask:0x5
	v_add_f32_dpp v102, v101, v101 row_half_mirror row_mask:0xf bank_mask:0xa
	v_fmac_f32_e32 v6, v94, v88
	v_fmac_f32_e32 v7, v94, v89
	v_add_f32_dpp v102, v102, v102 quad_perm:[1,0,3,2] row_mask:0xf bank_mask:0xf
	v_fma_f32 v4, -v108, v82, v4
	v_fma_f32 v5, -v108, v83, v5
	v_fma_f32 v6, -v108, v84, v6
	v_fma_f32 v7, -v108, v85, v7
	v_add_f32_dpp v102, v102, v102 quad_perm:[2,3,0,1] row_mask:0xf bank_mask:0xf
	s_waitcnt lgkmcnt(5)
; __device__ __forceinline__ float scan_step_asm(float4& S, const StepIn& s) {
;     float o, d1, d2, t;
;     asm volatile(
;         "v_mul_f32 %5, %0, %8\n\t"  "v_mul_f32 %6, %0, %12\n\t"
;         "v_fmac_f32 %5, %1, %9\n\t" "v_fmac_f32 %6, %1, %13\n\t"
;         "v_fmac_f32 %5, %2, %10\n\t" "v_fmac_f32 %6, %2, %14\n\t"
;         "v_fmac_f32 %5, %3, %11\n\t" "v_fmac_f32 %6, %3, %15\n\t"
;         "v_mul_f32 %0, %0, %16\n\t" "v_mul_f32 %1, %1, %17\n\t"
;         "v_add_f32_dpp %5, %5, %5 quad_perm:[1,0,3,2] row_mask:0xf bank_mask:0xf\n\t"
;         "v_add_f32_dpp %6, %6, %6 quad_perm:[1,0,3,2] row_mask:0xf bank_mask:0xf\n\t"
;         "v_mul_f32 %2, %2, %18\n\t" "v_mul_f32 %3, %3, %19\n\t"
;         "v_add_f32_dpp %5, %5, %5 quad_perm:[2,3,0,1] row_mask:0xf bank_mask:0xf\n\t"
;         "v_add_f32_dpp %6, %6, %6 quad_perm:[2,3,0,1] row_mask:0xf bank_mask:0xf\n\t"
;         "v_fmac_f32 %0, %28, %20\n\t" "v_fmac_f32 %1, %28, %21\n\t"
;         "v_add_f32_dpp %5, %5, %5 row_ror:4 row_mask:0xf bank_mask:0xf\n\t"
;         "v_add_f32_dpp %6, %6, %6 row_ror:4 row_mask:0xf bank_mask:0xf\n\t"
;         "v_fmac_f32 %2, %28, %22\n\t" "v_fmac_f32 %3, %28, %23\n\t"
;         "v_add_f32_dpp %5, %5, %5 row_ror:8 row_mask:0xf bank_mask:0xf\n\t"
;         "v_add_f32_dpp %6, %6, %6 row_ror:8 row_mask:0xf bank_mask:0xf\n\t"
;         "v_fma_f32 %4, %28, %30, %6\n\t"
; __device__ __forceinline__ void scan_prompt_wave(const Params& P, unsigned char* lds, int b, int h, int quarter) {
;     ...
;         for (int c = 0; c < NCH; ++c) {
;             const float* bp = (const float*)(lds + (c % SC_NB) * SC_BUF); const float* bpn = (const float*)(lds + ((c + 1) % SC_NB) * SC_BUF);
;             float ov = 0.f;
; #pragma unroll
;             for (int s = 0; s < SCH; ++s) {
;                 if (s == SCH - 3 && c + 1 < NCH) { while (scw[0] < (unsigned)(c + 2)) __builtin_amdgcn_s_sleep(1); asm volatile("" ::: "memory"); }
;                 lds_load_step(r[(s + 3) & 3], (s + 3 < SCH) ? bp + (s + 3) * RSB_BLK : bpn + (s + 3 - SCH) * RSB_BLK, c0, rl); __builtin_amdgcn_sched_barrier(0);
;                 const float o = scan_step_asm(S, r[s & 3]); __builtin_amdgcn_sched_barrier(0);
;                 ov = (cl == s) ? o : ov;
;             }
;             op[(size_t)cl * RW] = ov;
	ds_read_b128 v[74:77], v110 offset:10864
	ds_read_b128 v[90:93], v110 offset:11888
	ds_read_b128 v[78:81], v110 offset:11120
	ds_read_b32 v94, v111 offset:12144
	ds_read_b128 v[86:89], v110 offset:11632
	ds_read_b128 v[82:85], v110 offset:11376
	v_mul_f32_e32 v108, v4, v8
	v_fmac_f32_e32 v108, v5, v9
	v_fmac_f32_e32 v108, v6, v10
	v_fmac_f32_e32 v108, v7, v11
	v_mul_f32_e32 v96, v4, v24
	v_fmac_f32_e32 v96, v5, v25
	v_add_f32_dpp v108, v108, v108 quad_perm:[1,0,3,2] row_mask:0xf bank_mask:0xf
	v_fmac_f32_e32 v96, v6, v26
	v_fmac_f32_e32 v96, v7, v27
	v_add_f32_dpp v108, v108, v108 quad_perm:[2,3,0,1] row_mask:0xf bank_mask:0xf
	v_fmac_f32_e32 v4, v28, v20
	v_fmac_f32_e32 v5, v28, v21
	v_add_f32_dpp v108, v108, v108 row_ror:4 row_mask:0xf bank_mask:0xf
	v_fmac_f32_e32 v6, v28, v22
	v_fmac_f32_e32 v7, v28, v23
	v_add_f32_dpp v108, v108, v108 row_ror:8 row_mask:0xf bank_mask:0xf
	v_fma_f32 v4, -v108, v16, v4
	v_fma_f32 v5, -v108, v17, v5
	v_fma_f32 v6, -v108, v18, v6
	v_fma_f32 v7, -v108, v19, v7
	ds_read_b128 v[8:11], v110 offset:12416
	ds_read_b128 v[24:27], v110 offset:13440
	ds_read_b32 v28, v111 offset:13696
	ds_read_b128 v[20:23], v110 offset:13184
	ds_read_b128 v[16:19], v110 offset:12928
	v_mul_f32_e32 v108, v4, v30
	v_fmac_f32_e32 v108, v5, v31
	v_fmac_f32_e32 v108, v6, v32
	v_fmac_f32_e32 v108, v7, v33
	v_mul_f32_e32 v97, v4, v46
	v_fmac_f32_e32 v97, v5, v47
	v_add_f32_dpp v108, v108, v108 quad_perm:[1,0,3,2] row_mask:0xf bank_mask:0xf
	v_fmac_f32_e32 v97, v6, v48
	v_fmac_f32_e32 v97, v7, v49
	v_add_f32_dpp v108, v108, v108 quad_perm:[2,3,0,1] row_mask:0xf bank_mask:0xf
	v_fmac_f32_e32 v4, v50, v42
	v_fmac_f32_e32 v5, v50, v43
	v_add_f32_dpp v108, v108, v108 row_ror:4 row_mask:0xf bank_mask:0xf
	v_fmac_f32_e32 v6, v50, v44
	v_fmac_f32_e32 v7, v50, v45
	v_add_f32_dpp v108, v108, v108 row_ror:8 row_mask:0xf bank_mask:0xf
	v_fma_f32 v4, -v108, v38, v4
	v_fma_f32 v5, -v108, v39, v5
	v_fma_f32 v6, -v108, v40, v6
	v_fma_f32 v7, -v108, v41, v7
	s_waitcnt lgkmcnt(5)
	ds_read_b128 v[30:33], v110 offset:13968
	ds_read_b128 v[46:49], v110 offset:14992
	ds_read_b32 v50, v111 offset:15248
	ds_read_b128 v[42:45], v110 offset:14736
	ds_read_b128 v[38:41], v110 offset:14480
	v_mul_f32_e32 v108, v4, v52
	v_fmac_f32_e32 v108, v5, v53
	v_fmac_f32_e32 v108, v6, v54
	v_fmac_f32_e32 v108, v7, v55
	v_mul_f32_e32 v98, v4, v68
	v_fmac_f32_e32 v98, v5, v69
	v_add_f32_dpp v108, v108, v108 quad_perm:[1,0,3,2] row_mask:0xf bank_mask:0xf
	v_fmac_f32_e32 v98, v6, v70
	v_fmac_f32_e32 v98, v7, v71
	v_add_f32_dpp v108, v108, v108 quad_perm:[2,3,0,1] row_mask:0xf bank_mask:0xf
	v_fmac_f32_e32 v4, v72, v64
	v_fmac_f32_e32 v5, v72, v65
	v_add_f32_dpp v108, v108, v108 row_ror:4 row_mask:0xf bank_mask:0xf
	v_fmac_f32_e32 v6, v72, v66
	v_fmac_f32_e32 v7, v72, v67
	v_add_f32_dpp v108, v108, v108 row_ror:8 row_mask:0xf bank_mask:0xf
	v_fma_f32 v4, -v108, v60, v4
	v_fma_f32 v5, -v108, v61, v5
	v_fma_f32 v6, -v108, v62, v6
	v_fma_f32 v7, -v108, v63, v7
	ds_read_b128 v[52:55], v110 offset:15520
	ds_read_b128 v[68:71], v110 offset:16544
	ds_read_b32 v72, v111 offset:16800
	ds_read_b128 v[64:67], v110 offset:16288
	ds_read_b128 v[60:63], v110 offset:16032
	v_mul_f32_e32 v108, v4, v74
	v_fmac_f32_e32 v108, v5, v75
	v_fmac_f32_e32 v108, v6, v76
	v_fmac_f32_e32 v108, v7, v77
	v_mul_f32_e32 v99, v4, v90
	v_fmac_f32_e32 v99, v5, v91
	v_add_f32_dpp v108, v108, v108 quad_perm:[1,0,3,2] row_mask:0xf bank_mask:0xf
	v_fmac_f32_e32 v99, v6, v92
	v_fmac_f32_e32 v99, v7, v93
	v_add_f32_dpp v108, v108, v108 quad_perm:[2,3,0,1] row_mask:0xf bank_mask:0xf
	v_add_f32_dpp v100, v96, v96 row_ror:8 row_mask:0xf bank_mask:0x3
	v_add_f32_dpp v100, v98, v98 row_ror:8 row_mask:0xf bank_mask:0xc
	v_add_f32_dpp v108, v108, v108 row_ror:4 row_mask:0xf bank_mask:0xf
	v_add_f32_dpp v101, v97, v97 row_ror:8 row_mask:0xf bank_mask:0x3
	v_add_f32_dpp v101, v99, v99 row_ror:8 row_mask:0xf bank_mask:0xc
	v_add_f32_dpp v108, v108, v108 row_ror:8 row_mask:0xf bank_mask:0xf
	v_fmac_f32_e32 v4, v94, v86
	v_fmac_f32_e32 v5, v94, v87
	v_add_f32_dpp v103, v100, v100 row_half_mirror row_mask:0xf bank_mask:0x5
	v_add_f32_dpp v103, v101, v101 row_half_mirror row_mask:0xf bank_mask:0xa
	v_fmac_f32_e32 v6, v94, v88
	v_fmac_f32_e32 v7, v94, v89
	v_add_f32_dpp v103, v103, v103 quad_perm:[1,0,3,2] row_mask:0xf bank_mask:0xf
	v_fma_f32 v4, -v108, v82, v4
	v_fma_f32 v5, -v108, v83, v5
	v_fma_f32 v6, -v108, v84, v6
	v_fma_f32 v7, -v108, v85, v7
	v_add_f32_dpp v103, v103, v103 quad_perm:[2,3,0,1] row_mask:0xf bank_mask:0xf
	v_mul_f32_e32 v4, v4, v78
	v_mul_f32_e32 v5, v5, v79
	v_mul_f32_e32 v6, v6, v80
	v_mul_f32_e32 v7, v7, v81
	s_waitcnt lgkmcnt(5)
; __device__ __forceinline__ float scan_step_asm(float4& S, const StepIn& s) {
;     float o, d1, d2, t;
;     asm volatile(
;         "v_mul_f32 %5, %0, %8\n\t"  "v_mul_f32 %6, %0, %12\n\t"
;         "v_fmac_f32 %5, %1, %9\n\t" "v_fmac_f32 %6, %1, %13\n\t"
;         "v_fmac_f32 %5, %2, %10\n\t" "v_fmac_f32 %6, %2, %14\n\t"
;         "v_fmac_f32 %5, %3, %11\n\t" "v_fmac_f32 %6, %3, %15\n\t"
;         "v_mul_f32 %0, %0, %16\n\t" "v_mul_f32 %1, %1, %17\n\t"
;         "v_add_f32_dpp %5, %5, %5 quad_perm:[1,0,3,2] row_mask:0xf bank_mask:0xf\n\t"
;         "v_add_f32_dpp %6, %6, %6 quad_perm:[1,0,3,2] row_mask:0xf bank_mask:0xf\n\t"
;         "v_mul_f32 %2, %2, %18\n\t" "v_mul_f32 %3, %3, %19\n\t"
;         "v_add_f32_dpp %5, %5, %5 quad_perm:[2,3,0,1] row_mask:0xf bank_mask:0xf\n\t"
;         "v_add_f32_dpp %6, %6, %6 quad_perm:[2,3,0,1] row_mask:0xf bank_mask:0xf\n\t"
;         "v_fmac_f32 %0, %28, %20\n\t" "v_fmac_f32 %1, %28, %21\n\t"
;         "v_add_f32_dpp %5, %5, %5 row_ror:4 row_mask:0xf bank_mask:0xf\n\t"
;         "v_add_f32_dpp %6, %6, %6 row_ror:4 row_mask:0xf bank_mask:0xf\n\t"
;         "v_fmac_f32 %2, %28, %22\n\t" "v_fmac_f32 %3, %28, %23\n\t"
;         "v_add_f32_dpp %5, %5, %5 row_ror:8 row_mask:0xf bank_mask:0xf\n\t"
;         "v_add_f32_dpp %6, %6, %6 row_ror:8 row_mask:0xf bank_mask:0xf\n\t"
;         "v_fma_f32 %4, %28, %30, %6\n\t"
; __device__ __forceinline__ void scan_prompt_wave(const Params& P, unsigned char* lds, int b, int h, int quarter) {
;     ...
;         for (int c = 0; c < NCH; ++c) {
;             const float* bp = (const float*)(lds + (c % SC_NB) * SC_BUF); const float* bpn = (const float*)(lds + ((c + 1) % SC_NB) * SC_BUF);
;             float ov = 0.f;
; #pragma unroll
;             for (int s = 0; s < SCH; ++s) {
;                 if (s == SCH - 3 && c + 1 < NCH) { while (scw[0] < (unsigned)(c + 2)) __builtin_amdgcn_s_sleep(1); asm volatile("" ::: "memory"); }
;                 lds_load_step(r[(s + 3) & 3], (s + 3 < SCH) ? bp + (s + 3) * RSB_BLK : bpn + (s + 3 - SCH) * RSB_BLK, c0, rl); __builtin_amdgcn_sched_barrier(0);
;                 const float o = scan_step_asm(S, r[s & 3]); __builtin_amdgcn_sched_barrier(0);
;                 ov = (cl == s) ? o : ov;
;             }
;             op[(size_t)cl * RW] = ov;
;             op += (size_t)SCH * RW;
;             if (lane == 0) scw[1 + wave] = (unsigned)(c + 1);
	ds_read_b128 v[74:77], v110 offset:17072
	ds_read_b128 v[90:93], v110 offset:18096
	ds_read_b32 v94, v111 offset:18352
	ds_read_b128 v[86:89], v110 offset:17840
	ds_read_b128 v[82:85], v110 offset:17584
	v_mul_f32_e32 v108, v4, v8
	v_fmac_f32_e32 v108, v5, v9
	v_fmac_f32_e32 v108, v6, v10
	v_fmac_f32_e32 v108, v7, v11
	v_mul_f32_e32 v96, v4, v24
	v_fmac_f32_e32 v96, v5, v25
	v_add_f32_dpp v108, v108, v108 quad_perm:[1,0,3,2] row_mask:0xf bank_mask:0xf
	v_fmac_f32_e32 v96, v6, v26
	v_fmac_f32_e32 v96, v7, v27
	v_add_f32_dpp v108, v108, v108 quad_perm:[2,3,0,1] row_mask:0xf bank_mask:0xf
	v_fmac_f32_e32 v4, v28, v20
	v_fmac_f32_e32 v5, v28, v21
	v_add_f32_dpp v108, v108, v108 row_ror:4 row_mask:0xf bank_mask:0xf
	v_fmac_f32_e32 v6, v28, v22
	v_fmac_f32_e32 v7, v28, v23
	v_add_f32_dpp v108, v108, v108 row_ror:8 row_mask:0xf bank_mask:0xf
	v_fma_f32 v4, -v108, v16, v4
	v_fma_f32 v5, -v108, v17, v5
	v_fma_f32 v6, -v108, v18, v6
	v_fma_f32 v7, -v108, v19, v7
	ds_read_b128 v[8:11], v110 offset:18624
	ds_read_b128 v[24:27], v110 offset:19648
	ds_read_b32 v28, v111 offset:19904
	ds_read_b128 v[20:23], v110 offset:19392
	ds_read_b128 v[16:19], v110 offset:19136
	ds_read_b32 v109, v118
	v_mul_f32_e32 v108, v4, v30
	v_fmac_f32_e32 v108, v5, v31
	v_fmac_f32_e32 v108, v6, v32
	v_fmac_f32_e32 v108, v7, v33
	v_mul_f32_e32 v97, v4, v46
	v_fmac_f32_e32 v97, v5, v47
	v_add_f32_dpp v108, v108, v108 quad_perm:[1,0,3,2] row_mask:0xf bank_mask:0xf
	v_fmac_f32_e32 v97, v6, v48
	v_fmac_f32_e32 v97, v7, v49
	v_add_f32_dpp v108, v108, v108 quad_perm:[2,3,0,1] row_mask:0xf bank_mask:0xf
	v_fmac_f32_e32 v4, v50, v42
	v_fmac_f32_e32 v5, v50, v43
	v_add_f32_dpp v108, v108, v108 row_ror:4 row_mask:0xf bank_mask:0xf
	v_fmac_f32_e32 v6, v50, v44
	v_fmac_f32_e32 v7, v50, v45
	v_add_f32_dpp v108, v108, v108 row_ror:8 row_mask:0xf bank_mask:0xf
	v_fma_f32 v4, -v108, v38, v4
	v_fma_f32 v5, -v108, v39, v5
	v_fma_f32 v6, -v108, v40, v6
	v_fma_f32 v7, -v108, v41, v7
	s_waitcnt lgkmcnt(6)
	ds_read_b128 v[30:33], v110 offset:20176
	ds_read_b128 v[46:49], v110 offset:21200
	ds_read_b32 v50, v111 offset:21456
	ds_read_b128 v[42:45], v110 offset:20944
	ds_read_b128 v[38:41], v110 offset:20688
	v_mul_f32_e32 v108, v4, v52
	v_fmac_f32_e32 v108, v5, v53
	v_fmac_f32_e32 v108, v6, v54
	v_fmac_f32_e32 v108, v7, v55
	v_mul_f32_e32 v98, v4, v68
	v_fmac_f32_e32 v98, v5, v69
	v_add_f32_dpp v108, v108, v108 quad_perm:[1,0,3,2] row_mask:0xf bank_mask:0xf
	v_fmac_f32_e32 v98, v6, v70
	v_fmac_f32_e32 v98, v7, v71
	v_add_f32_dpp v108, v108, v108 quad_perm:[2,3,0,1] row_mask:0xf bank_mask:0xf
	v_fmac_f32_e32 v4, v72, v64
	v_fmac_f32_e32 v5, v72, v65
	v_add_f32_dpp v108, v108, v108 row_ror:4 row_mask:0xf bank_mask:0xf
	v_fmac_f32_e32 v6, v72, v66
	v_fmac_f32_e32 v7, v72, v67
	v_add_f32_dpp v108, v108, v108 row_ror:8 row_mask:0xf bank_mask:0xf
	v_fma_f32 v4, -v108, v60, v4
	v_fma_f32 v5, -v108, v61, v5
	v_fma_f32 v6, -v108, v62, v6
	v_fma_f32 v7, -v108, v63, v7
	ds_read_b128 v[52:55], v110 offset:21728
	ds_read_b128 v[68:71], v110 offset:22752
	ds_read_b32 v72, v111 offset:23008
	ds_read_b128 v[64:67], v110 offset:22496
	ds_read_b128 v[60:63], v110 offset:22240
	v_mul_f32_e32 v108, v4, v74
	v_fmac_f32_e32 v108, v5, v75
	v_fmac_f32_e32 v108, v6, v76
	v_fmac_f32_e32 v108, v7, v77
	v_mul_f32_e32 v99, v4, v90
	v_fmac_f32_e32 v99, v5, v91
	v_add_f32_dpp v108, v108, v108 quad_perm:[1,0,3,2] row_mask:0xf bank_mask:0xf
	v_fmac_f32_e32 v99, v6, v92
	v_fmac_f32_e32 v99, v7, v93
	v_add_f32_dpp v108, v108, v108 quad_perm:[2,3,0,1] row_mask:0xf bank_mask:0xf
	v_add_f32_dpp v100, v96, v96 row_ror:8 row_mask:0xf bank_mask:0x3
	v_add_f32_dpp v100, v98, v98 row_ror:8 row_mask:0xf bank_mask:0xc
	v_add_f32_dpp v108, v108, v108 row_ror:4 row_mask:0xf bank_mask:0xf
	v_add_f32_dpp v101, v97, v97 row_ror:8 row_mask:0xf bank_mask:0x3
	v_add_f32_dpp v101, v99, v99 row_ror:8 row_mask:0xf bank_mask:0xc
	v_add_f32_dpp v108, v108, v108 row_ror:8 row_mask:0xf bank_mask:0xf
	v_fmac_f32_e32 v4, v94, v86
	v_fmac_f32_e32 v5, v94, v87
	v_add_f32_dpp v104, v100, v100 row_half_mirror row_mask:0xf bank_mask:0x5
	v_add_f32_dpp v104, v101, v101 row_half_mirror row_mask:0xf bank_mask:0xa
	v_fmac_f32_e32 v6, v94, v88
	v_fmac_f32_e32 v7, v94, v89
	v_add_f32_dpp v104, v104, v104 quad_perm:[1,0,3,2] row_mask:0xf bank_mask:0xf
	v_fma_f32 v4, -v108, v82, v4
	v_fma_f32 v5, -v108, v83, v5
	v_fma_f32 v6, -v108, v84, v6
	v_fma_f32 v7, -v108, v85, v7
	v_add_f32_dpp v104, v104, v104 quad_perm:[2,3,0,1] row_mask:0xf bank_mask:0xf
	s_waitcnt lgkmcnt(5)
	ds_read_b128 v[74:77], v110 offset:23280
	ds_read_b128 v[90:93], v110 offset:24304
	ds_read_b128 v[78:81], v110 offset:23536
	ds_read_b32 v94, v111 offset:24560
	ds_read_b128 v[86:89], v110 offset:24048
	ds_read_b128 v[82:85], v110 offset:23792
	v_add_u32_e32 v106, s4, v116
	v_add_u32_e32 v107, s4, v117
	s_add_i32 s7, s42, 1
	v_mov_b32_e32 v120, s7
	ds_read_b32 v106, v106 offset:1280
	ds_read_b32 v107, v107 offset:1540
	ds_write_b32 v119, v120
	v_mul_f32_e32 v108, v4, v8
	v_fmac_f32_e32 v108, v5, v9
	v_fmac_f32_e32 v108, v6, v10
	v_fmac_f32_e32 v108, v7, v11
	v_mul_f32_e32 v96, v4, v24
	v_fmac_f32_e32 v96, v5, v25
	v_add_f32_dpp v108, v108, v108 quad_perm:[1,0,3,2] row_mask:0xf bank_mask:0xf
	v_fmac_f32_e32 v96, v6, v26
	v_fmac_f32_e32 v96, v7, v27
	v_add_f32_dpp v108, v108, v108 quad_perm:[2,3,0,1] row_mask:0xf bank_mask:0xf
	v_fmac_f32_e32 v4, v28, v20
	v_fmac_f32_e32 v5, v28, v21
	v_add_f32_dpp v108, v108, v108 row_ror:4 row_mask:0xf bank_mask:0xf
	v_fmac_f32_e32 v6, v28, v22
	v_fmac_f32_e32 v7, v28, v23
	v_add_f32_dpp v108, v108, v108 row_ror:8 row_mask:0xf bank_mask:0xf
	v_fma_f32 v4, -v108, v16, v4
	v_fma_f32 v5, -v108, v17, v5
	v_fma_f32 v6, -v108, v18, v6
	v_fma_f32 v7, -v108, v19, v7
	v_cmp_le_u32_e32 vcc, s6, v109
	s_cbranch_vccnz .Lscan_landed

; __device__ __forceinline__ float scan_step_asm(float4& S, const StepIn& s) {
;     float o, d1, d2, t;
;     asm volatile(
;         "v_mul_f32 %5, %0, %8\n\t"  "v_mul_f32 %6, %0, %12\n\t"
;         "v_fmac_f32 %5, %1, %9\n\t" "v_fmac_f32 %6, %1, %13\n\t"
;         "v_fmac_f32 %5, %2, %10\n\t" "v_fmac_f32 %6, %2, %14\n\t"
;         "v_fmac_f32 %5, %3, %11\n\t" "v_fmac_f32 %6, %3, %15\n\t"
;         "v_mul_f32 %0, %0, %16\n\t" "v_mul_f32 %1, %1, %17\n\t"
;         "v_add_f32_dpp %5, %5, %5 quad_perm:[1,0,3,2] row_mask:0xf bank_mask:0xf\n\t"
;         "v_add_f32_dpp %6, %6, %6 quad_perm:[1,0,3,2] row_mask:0xf bank_mask:0xf\n\t"
;         "v_mul_f32 %2, %2, %18\n\t" "v_mul_f32 %3, %3, %19\n\t"
;         "v_add_f32_dpp %5, %5, %5 quad_perm:[2,3,0,1] row_mask:0xf bank_mask:0xf\n\t"
;         "v_add_f32_dpp %6, %6, %6 quad_perm:[2,3,0,1] row_mask:0xf bank_mask:0xf\n\t"
;         "v_fmac_f32 %0, %28, %20\n\t" "v_fmac_f32 %1, %28, %21\n\t"
;         "v_add_f32_dpp %5, %5, %5 row_ror:4 row_mask:0xf bank_mask:0xf\n\t"
;         "v_add_f32_dpp %6, %6, %6 row_ror:4 row_mask:0xf bank_mask:0xf\n\t"
;         "v_fmac_f32 %2, %28, %22\n\t" "v_fmac_f32 %3, %28, %23\n\t"
;         "v_add_f32_dpp %5, %5, %5 row_ror:8 row_mask:0xf bank_mask:0xf\n\t"
;         "v_add_f32_dpp %6, %6, %6 row_ror:8 row_mask:0xf bank_mask:0xf\n\t"
;         "v_fma_f32 %4, %28, %30, %6\n\t"
;         "v_fma_f32 %0, -%5, %24, %0\n\t" "v_fma_f32 %1, -%5, %25, %1\n\t" "v_fma_f32 %2, -%5, %26, %2\n\t" "v_fma_f32 %3, -%5, %27, %3\n\t"
;         "s_nop 0"
; __device__ __forceinline__ void scan_prompt_wave(const Params& P, unsigned char* lds, int b, int h, int quarter) {
;     ...
;             for (int s = 0; s < SCH; ++s) {
;                 if (s == SCH - 3 && c + 1 < NCH) { while (scw[0] < (unsigned)(c + 2)) __builtin_amdgcn_s_sleep(1); asm volatile("" ::: "memory"); }
;                 lds_load_step(r[(s + 3) & 3], (s + 3 < SCH) ? bp + (s + 3) * RSB_BLK : bpn + (s + 3 - SCH) * RSB_BLK, c0, rl); __builtin_amdgcn_sched_barrier(0);
;                 const float o = scan_step_asm(S, r[s & 3]); __builtin_amdgcn_sched_barrier(0);
;                 ov = (cl == s) ? o : ov;
;             }
;             op[(size_t)cl * RW] = ov;
;             op += (size_t)SCH * RW;
;             if (lane == 0) scw[1 + wave] = (unsigned)(c + 1);
.Lscan_landed:
	ds_read_b128 v[8:11], v112
	ds_read_b128 v[24:27], v112 offset:1024
	ds_read_b32 v28, v113 offset:1280
	ds_read_b128 v[20:23], v112 offset:768
	ds_read_b128 v[16:19], v112 offset:512
	v_mul_f32_e32 v108, v4, v30
	v_fmac_f32_e32 v108, v5, v31
	v_fmac_f32_e32 v108, v6, v32
	v_fmac_f32_e32 v108, v7, v33
	v_mul_f32_e32 v97, v4, v46
	v_fmac_f32_e32 v97, v5, v47
	v_add_f32_dpp v108, v108, v108 quad_perm:[1,0,3,2] row_mask:0xf bank_mask:0xf
	v_fmac_f32_e32 v97, v6, v48
	v_fmac_f32_e32 v97, v7, v49
	v_add_f32_dpp v108, v108, v108 quad_perm:[2,3,0,1] row_mask:0xf bank_mask:0xf
	v_fmac_f32_e32 v4, v50, v42
	v_fmac_f32_e32 v5, v50, v43
	v_add_f32_dpp v108, v108, v108 row_ror:4 row_mask:0xf bank_mask:0xf
	v_fmac_f32_e32 v6, v50, v44
	v_fmac_f32_e32 v7, v50, v45
	v_add_f32_dpp v108, v108, v108 row_ror:8 row_mask:0xf bank_mask:0xf
	v_fma_f32 v4, -v108, v38, v4
	v_fma_f32 v5, -v108, v39, v5
	v_fma_f32 v6, -v108, v40, v6
	v_fma_f32 v7, -v108, v41, v7
	s_waitcnt lgkmcnt(8)
	ds_read_b128 v[30:33], v112 offset:1552
	ds_read_b128 v[46:49], v112 offset:2576
	ds_read_b32 v50, v113 offset:2832
	ds_read_b128 v[42:45], v112 offset:2320
	ds_read_b128 v[38:41], v112 offset:2064
	v_mul_f32_e32 v108, v4, v52
	v_fmac_f32_e32 v108, v5, v53
	v_fmac_f32_e32 v108, v6, v54
	v_fmac_f32_e32 v108, v7, v55
	v_mul_f32_e32 v98, v4, v68
	v_fmac_f32_e32 v98, v5, v69
	v_add_f32_dpp v108, v108, v108 quad_perm:[1,0,3,2] row_mask:0xf bank_mask:0xf
	v_fmac_f32_e32 v98, v6, v70
	v_fmac_f32_e32 v98, v7, v71
	v_add_f32_dpp v108, v108, v108 quad_perm:[2,3,0,1] row_mask:0xf bank_mask:0xf
	v_fmac_f32_e32 v4, v72, v64
	v_fmac_f32_e32 v5, v72, v65
	v_add_f32_dpp v108, v108, v108 row_ror:4 row_mask:0xf bank_mask:0xf
	v_fmac_f32_e32 v6, v72, v66
	v_fmac_f32_e32 v7, v72, v67
	v_add_f32_dpp v108, v108, v108 row_ror:8 row_mask:0xf bank_mask:0xf
	v_fma_f32 v4, -v108, v60, v4
	v_fma_f32 v5, -v108, v61, v5
	v_fma_f32 v6, -v108, v62, v6
	v_fma_f32 v7, -v108, v63, v7
	ds_read_b128 v[52:55], v112 offset:3104
	ds_read_b128 v[68:71], v112 offset:4128
	ds_read_b32 v72, v113 offset:4384
	ds_read_b128 v[64:67], v112 offset:3872
	ds_read_b128 v[60:63], v112 offset:3616
	v_mul_f32_e32 v108, v4, v74
	v_fmac_f32_e32 v108, v5, v75
	v_fmac_f32_e32 v108, v6, v76
	v_fmac_f32_e32 v108, v7, v77
	v_mul_f32_e32 v99, v4, v90
	v_fmac_f32_e32 v99, v5, v91
	v_add_f32_dpp v108, v108, v108 quad_perm:[1,0,3,2] row_mask:0xf bank_mask:0xf
	v_fmac_f32_e32 v99, v6, v92
	v_fmac_f32_e32 v99, v7, v93
	v_add_f32_dpp v108, v108, v108 quad_perm:[2,3,0,1] row_mask:0xf bank_mask:0xf
	v_add_f32_dpp v100, v96, v96 row_ror:8 row_mask:0xf bank_mask:0x3
	v_add_f32_dpp v100, v98, v98 row_ror:8 row_mask:0xf bank_mask:0xc
	v_add_f32_dpp v108, v108, v108 row_ror:4 row_mask:0xf bank_mask:0xf
	v_add_f32_dpp v101, v97, v97 row_ror:8 row_mask:0xf bank_mask:0x3
	v_add_f32_dpp v101, v99, v99 row_ror:8 row_mask:0xf bank_mask:0xc
	v_add_f32_dpp v108, v108, v108 row_ror:8 row_mask:0xf bank_mask:0xf
	v_fmac_f32_e32 v4, v94, v86
	v_fmac_f32_e32 v5, v94, v87
	v_add_f32_dpp v105, v100, v100 row_half_mirror row_mask:0xf bank_mask:0x5
	v_add_f32_dpp v105, v101, v101 row_half_mirror row_mask:0xf bank_mask:0xa
	v_fmac_f32_e32 v6, v94, v88
	v_fmac_f32_e32 v7, v94, v89
	v_add_f32_dpp v105, v105, v105 quad_perm:[1,0,3,2] row_mask:0xf bank_mask:0xf
	v_fma_f32 v4, -v108, v82, v4
	v_fma_f32 v5, -v108, v83, v5
	v_fma_f32 v6, -v108, v84, v6
	v_fma_f32 v7, -v108, v85, v7
	v_add_f32_dpp v105, v105, v105 quad_perm:[2,3,0,1] row_mask:0xf bank_mask:0xf
	v_mul_f32_e32 v4, v4, v78
	v_mul_f32_e32 v5, v5, v79
	v_mul_f32_e32 v6, v6, v80
	v_mul_f32_e32 v7, v7, v81
	v_cndmask_b32_e64 v102, v102, v103, s[8:9]
	v_cndmask_b32_e64 v102, v102, v104, s[10:11]
	s_add_i32 s42, s42, 1
	s_mov_b32 s4, s5
	s_add_i32 s5, s5, 0x7000
	v_cndmask_b32_e64 v102, v102, v105, s[12:13]
	s_waitcnt lgkmcnt(15)
	s_cmp_eq_u32 s5, 0x23000
	s_cselect_b32 s5, 0, s5
	v_fmac_f32_e32 v102, v106, v107
	s_add_i32 s6, s42, 2
	s_min_u32 s6, s6, 0x100
	global_store_dword v[122:123], v102, off
	v_mov_b32_e32 v110, v112
	v_mov_b32_e32 v111, v113
	v_add_u32_e32 v112, s5, v114
	v_add_u32_e32 v113, s5, v115
	v_lshl_add_u64 v[122:123], v[122:123], 0, s[0:1]
	s_cmpk_lg_i32 s42, 0x100
	s_cbranch_scc1 .Lscan_chunk
	s_waitcnt lgkmcnt(0)
	v_mov_b32_e32 v2, v4
	v_mov_b32_e32 v98, v5
	v_mov_b32_e32 v99, v6
	v_mov_b32_e32 v100, v7
	v_lshrrev_b32_e32 v88, 2, v115
	v_mov_b32_e32 v89, 0
	v_lshrrev_b32_e32 v3, 2, v114
	s_branch .LBB0_1249

; __global__ void __launch_bounds__(512, 2) mk_fwd(Params P) {
;     extern __shared__ __attribute__((aligned(16))) unsigned char lds[];
	.amdhsa_kernel _Z6mk_fwd6Params
		.amdhsa_group_segment_fixed_size 0
		.amdhsa_private_segment_fixed_size 0
		.amdhsa_kernarg_size 504
		.amdhsa_user_sgpr_count 2
		.amdhsa_user_sgpr_dispatch_ptr 0
		.amdhsa_user_sgpr_queue_ptr 0
		.amdhsa_user_sgpr_kernarg_segment_ptr 1
		.amdhsa_user_sgpr_dispatch_id 0
		.amdhsa_user_sgpr_kernarg_preload_length 0
		.amdhsa_user_sgpr_kernarg_preload_offset 0
		.amdhsa_user_sgpr_private_segment_size 0
		.amdhsa_uses_dynamic_stack 0
		.amdhsa_enable_private_segment 0
		.amdhsa_system_sgpr_workgroup_id_x 1
		.amdhsa_system_sgpr_workgroup_id_y 0
		.amdhsa_system_sgpr_workgroup_id_z 0
		.amdhsa_system_sgpr_workgroup_info 0
		.amdhsa_system_vgpr_workitem_id 0
		.amdhsa_next_free_vgpr 256
		.amdhsa_next_free_sgpr 102
		.amdhsa_accum_offset 256
		.amdhsa_reserve_vcc 1
		.amdhsa_float_round_mode_32 0
		.amdhsa_float_round_mode_16_64 0
		.amdhsa_float_denorm_mode_32 3
		.amdhsa_float_denorm_mode_16_64 3
		.amdhsa_dx10_clamp 1
		.amdhsa_ieee_mode 1
		.amdhsa_fp16_overflow 0
		.amdhsa_tg_split 0
		.amdhsa_exception_fp_ieee_invalid_op 0
		.amdhsa_exception_fp_denorm_src 0
		.amdhsa_exception_fp_ieee_div_zero 0
		.amdhsa_exception_fp_ieee_overflow 0
		.amdhsa_exception_fp_ieee_underflow 0
		.amdhsa_exception_fp_ieee_inexact 0
		.amdhsa_exception_int_div_zero 0
	.end_amdhsa_kernel

; __global__ void __launch_bounds__(512, 2) mk_fwd(Params P) {
;     extern __shared__ __attribute__((aligned(16))) unsigned char lds[];
amdhsa.kernels:
  - .agpr_count:     0
    .args:
      - .offset:         0
        .size:           248
        .value_kind:     by_value
      - .offset:         248
        .size:           4
        .value_kind:     hidden_block_count_x
      - .offset:         252
        .size:           4
        .value_kind:     hidden_block_count_y
      - .offset:         256
        .size:           4
        .value_kind:     hidden_block_count_z
      - .offset:         260
        .size:           2
        .value_kind:     hidden_group_size_x
      - .offset:         262
        .size:           2
        .value_kind:     hidden_group_size_y
      - .offset:         264
        .size:           2
        .value_kind:     hidden_group_size_z
      - .offset:         266
        .size:           2
        .value_kind:     hidden_remainder_x
      - .offset:         268
        .size:           2
        .value_kind:     hidden_remainder_y
      - .offset:         270
        .size:           2
        .value_kind:     hidden_remainder_z
      - .offset:         288
        .size:           8
        .value_kind:     hidden_global_offset_x
      - .offset:         296
        .size:           8
        .value_kind:     hidden_global_offset_y
      - .offset:         304
        .size:           8
        .value_kind:     hidden_global_offset_z
      - .offset:         312
        .size:           2
        .value_kind:     hidden_grid_dims
      - .offset:         368
        .size:           4
        .value_kind:     hidden_dynamic_lds_size
    .group_segment_fixed_size: 0
    .kernarg_segment_align: 8
    .kernarg_segment_size: 504
    .language:       OpenCL C
    .language_version:
      - 2
      - 0
    .max_flat_workgroup_size: 512
    .name:           _Z6mk_fwd6Params
    .private_segment_fixed_size: 0
    .sgpr_count:     108
    .sgpr_spill_count: 76
    .symbol:         _Z6mk_fwd6Params.kd
    .uniform_work_group_size: 1
    .uses_dynamic_stack: false
    .vgpr_count:     256
    .vgpr_spill_count: 0
    .wavefront_size: 64
